# wave-sum butterflies in the norm phases via v_permlane32/16_swap + DPP row_ror adds instead of six ds_bpermute round trips (bit-identical sums)
# baseline (speedup 1.0000x reference)
; __device__ __forceinline__ int get_bid() { return 2 * get_rbid() + get_hb(); }
; template <bool PART, bool SRC16 = false>
; __device__ __forceinline__ void normmod_row2(const void* __restrict__ srcv, const float* __restrict__ g, const float* __restrict__ sh, const float* __restrict__ sc, bf16_t* __restrict__ dst, int lane, const float* __restrict__ bsh = nullptr) {
;   f32x4 v[2][4]; float ss0 = 0.f, ss1 = 0.f;
; #pragma unroll
;   for (int i = 0; i < 4; ++i) {
;     if (SRC16) { v[0][i] = ld4_bf16((const bf16_t*)srcv + lane * 4 + 256 * i); v[1][i] = ld4_bf16((const bf16_t*)srcv + 1024 + lane * 4 + 256 * i); }
;     else { v[0][i] = __builtin_nontemporal_load((const f32x4*)((const float*)srcv + lane * 4 + 256 * i)); v[1][i] = __builtin_nontemporal_load((const f32x4*)((const float*)srcv + 1024 + lane * 4 + 256 * i)); }
;   }
; #pragma unroll
;   for (int i = 0; i < 4; ++i) {
;     ss0 += v[0][i][0] * v[0][i][0] + v[0][i][1] * v[0][i][1] + v[0][i][2] * v[0][i][2] + v[0][i][3] * v[0][i][3];
;     ss1 += v[1][i][0] * v[1][i][0] + v[1][i][1] * v[1][i][1] + v[1][i][2] * v[1][i][2] + v[1][i][3] * v[1][i][3];
;   }
;   ss0 = wave_sum(ss0); ss1 = wave_sum(ss1);
;   const float r0 = rsqrtf(ss0 * (1.0f / 1024.0f) + 1e-6f), r1 = rsqrtf(ss1 * (1.0f / 1024.0f) + 1e-6f);
; #pragma unroll
;   for (int i = 0; i < 4; ++i) {
;     const int k = lane * 4 + 256 * i;
;     const f32x4 g4 = *(const f32x4*)(g + k);
;     f32x4 s4 = *(const f32x4*)(sh + k), c4 = *(const f32x4*)(sc + k);
;     if (PART) {
; #pragma unroll
;       for (int q = 1; q < 4; ++q) { s4 += *(const f32x4*)(sh + (size_t)q * 110592 + k); c4 += *(const f32x4*)(sc + (size_t)q * 110592 + k); }
;       s4 += *(const f32x4*)(bsh + k); c4 += *(const f32x4*)(bsh + 1024 + k);
; __device__ __forceinline__ void phase_normmod_kv(CP& p) {
;     ...
;   for (int r = (get_bid() * 4 + wv) * 2; r < 18432; r += VGRID * 8) {
;     const int b = r / 2304, pp = r - b * 2304;
;     const float* src; const float* mv;
;     if (pp < 256) { src = p.ctx + ((size_t)b * 256 + pp) * 1024; mv = p.modp + (size_t)8 * 6144; }
;     else { src = p.x + ((size_t)b * 2048 + pp - 256) * 1024; mv = p.modp + (size_t)b * 6144; }
;     normmod_row2<true>(src, g, mv, mv + 1024, p.hxc + (size_t)r * 1024, lane, p.mod_b);
.Lp1_go:
	s_add_u32 s10, s18, 0x1000
	s_addc_u32 s11, s19, 0
	global_load_dwordx4 v[64:67], v3, s[24:25] nt
	global_load_dwordx4 v[68:71], v3, s[24:25] offset:1024 nt
	global_load_dwordx4 v[72:75], v3, s[24:25] offset:2048 nt
	global_load_dwordx4 v[76:79], v3, s[24:25] offset:3072 nt
	s_add_u32 s24, s24, 0x1000
	s_addc_u32 s25, s25, 0
	global_load_dwordx4 v[80:83], v3, s[24:25] nt
	global_load_dwordx4 v[84:87], v3, s[24:25] offset:1024 nt
	global_load_dwordx4 v[88:91], v3, s[24:25] offset:2048 nt
	global_load_dwordx4 v[92:95], v3, s[24:25] offset:3072 nt
	s_add_u32 s24, s24, 0x1000
	s_addc_u32 s25, s25, 0
	s_add_u32 s16, s28, 0x1000
	s_addc_u32 s17, s29, 0
	global_load_dwordx4 v[112:115], v3, s[4:5]
	global_load_dwordx4 v[116:119], v3, s[18:19]
	global_load_dwordx4 v[120:123], v3, s[10:11]
	global_load_dwordx4 v[124:127], v3, s[28:29]
	global_load_dwordx4 v[128:131], v13, s[28:29]
	global_load_dwordx4 v[132:135], v14, s[28:29]
	global_load_dwordx4 v[136:139], v15, s[28:29]
	global_load_dwordx4 v[140:143], v3, s[16:17]
	global_load_dwordx4 v[144:147], v13, s[16:17]
	global_load_dwordx4 v[148:151], v14, s[16:17]
	global_load_dwordx4 v[152:155], v15, s[16:17]
	global_load_dwordx4 v[156:159], v3, s[4:5] offset:1024
	global_load_dwordx4 v[160:163], v3, s[18:19] offset:1024
	global_load_dwordx4 v[164:167], v3, s[10:11] offset:1024
	global_load_dwordx4 v[168:171], v3, s[28:29] offset:1024
	global_load_dwordx4 v[172:175], v13, s[28:29] offset:1024
	global_load_dwordx4 v[176:179], v14, s[28:29] offset:1024
	global_load_dwordx4 v[180:183], v15, s[28:29] offset:1024
	global_load_dwordx4 v[184:187], v3, s[16:17] offset:1024
	global_load_dwordx4 v[188:191], v13, s[16:17] offset:1024
	global_load_dwordx4 v[192:195], v14, s[16:17] offset:1024
	global_load_dwordx4 v[196:199], v15, s[16:17] offset:1024
	s_waitcnt vmcnt(0)
	v_pk_add_f32 v[48:49], v[124:125], v[128:129]
	v_pk_add_f32 v[48:49], v[48:49], v[132:133]
	v_pk_add_f32 v[48:49], v[48:49], v[136:137]
	v_pk_add_f32 v[32:33], v[140:141], v[144:145]
	v_pk_add_f32 v[32:33], v[32:33], v[148:149]
	v_pk_add_f32 v[32:33], v[32:33], v[152:153]
	v_pk_add_f32 v[50:51], v[126:127], v[130:131]
	v_pk_add_f32 v[50:51], v[50:51], v[134:135]
	v_pk_add_f32 v[50:51], v[50:51], v[138:139]
	v_pk_add_f32 v[34:35], v[142:143], v[146:147]
	v_pk_add_f32 v[34:35], v[34:35], v[150:151]
	v_pk_add_f32 v[34:35], v[34:35], v[154:155]
	v_add_f32_e32 v48, v116, v48
	v_add_f32_e32 v32, v120, v32
	v_add_f32_e32 v32, 1.0, v32
	v_mul_f32_e32 v32, v112, v32
	v_add_f32_e32 v49, v117, v49
	v_add_f32_e32 v33, v121, v33
	v_add_f32_e32 v33, 1.0, v33
	v_mul_f32_e32 v33, v113, v33
	v_add_f32_e32 v50, v118, v50
	v_add_f32_e32 v34, v122, v34
	v_add_f32_e32 v34, 1.0, v34
	v_mul_f32_e32 v34, v114, v34
	v_add_f32_e32 v51, v119, v51
	v_add_f32_e32 v35, v123, v35
	v_add_f32_e32 v35, 1.0, v35
	v_mul_f32_e32 v35, v115, v35
	v_pk_add_f32 v[52:53], v[168:169], v[172:173]
	v_pk_add_f32 v[52:53], v[52:53], v[176:177]
	v_pk_add_f32 v[52:53], v[52:53], v[180:181]
	v_pk_add_f32 v[36:37], v[184:185], v[188:189]
	v_pk_add_f32 v[36:37], v[36:37], v[192:193]
	v_pk_add_f32 v[36:37], v[36:37], v[196:197]
	v_pk_add_f32 v[54:55], v[170:171], v[174:175]
	v_pk_add_f32 v[54:55], v[54:55], v[178:179]
	v_pk_add_f32 v[54:55], v[54:55], v[182:183]
	v_pk_add_f32 v[38:39], v[186:187], v[190:191]
	v_pk_add_f32 v[38:39], v[38:39], v[194:195]
	v_pk_add_f32 v[38:39], v[38:39], v[198:199]
	v_add_f32_e32 v52, v160, v52
	v_add_f32_e32 v36, v164, v36
	v_add_f32_e32 v36, 1.0, v36
	v_mul_f32_e32 v36, v156, v36
	v_add_f32_e32 v53, v161, v53
	v_add_f32_e32 v37, v165, v37
	v_add_f32_e32 v37, 1.0, v37
	v_mul_f32_e32 v37, v157, v37
	v_add_f32_e32 v54, v162, v54
	v_add_f32_e32 v38, v166, v38
	v_add_f32_e32 v38, 1.0, v38
	v_mul_f32_e32 v38, v158, v38
	v_add_f32_e32 v55, v163, v55
	v_add_f32_e32 v39, v167, v39
	v_add_f32_e32 v39, 1.0, v39
	v_mul_f32_e32 v39, v159, v39
	global_load_dwordx4 v[112:115], v3, s[4:5] offset:2048
	global_load_dwordx4 v[116:119], v3, s[18:19] offset:2048
	global_load_dwordx4 v[120:123], v3, s[10:11] offset:2048
	global_load_dwordx4 v[124:127], v3, s[28:29] offset:2048
	global_load_dwordx4 v[128:131], v13, s[28:29] offset:2048
	global_load_dwordx4 v[132:135], v14, s[28:29] offset:2048
	global_load_dwordx4 v[136:139], v15, s[28:29] offset:2048
	global_load_dwordx4 v[140:143], v3, s[16:17] offset:2048
	global_load_dwordx4 v[144:147], v13, s[16:17] offset:2048
	global_load_dwordx4 v[148:151], v14, s[16:17] offset:2048
	global_load_dwordx4 v[152:155], v15, s[16:17] offset:2048
	global_load_dwordx4 v[156:159], v3, s[4:5] offset:3072
	global_load_dwordx4 v[160:163], v3, s[18:19] offset:3072
	global_load_dwordx4 v[164:167], v3, s[10:11] offset:3072
	global_load_dwordx4 v[168:171], v3, s[28:29] offset:3072
	global_load_dwordx4 v[172:175], v13, s[28:29] offset:3072
	global_load_dwordx4 v[176:179], v14, s[28:29] offset:3072
	global_load_dwordx4 v[180:183], v15, s[28:29] offset:3072
	global_load_dwordx4 v[184:187], v3, s[16:17] offset:3072
	global_load_dwordx4 v[188:191], v13, s[16:17] offset:3072
	global_load_dwordx4 v[192:195], v14, s[16:17] offset:3072
	global_load_dwordx4 v[196:199], v15, s[16:17] offset:3072
	s_waitcnt vmcnt(0)
; __device__ __forceinline__ unsigned pack2(float a, float b) { unsigned r; asm("v_cvt_pk_bf16_f32 %0, %1, %2" : "=v"(r) : "v"(a), "v"(b)); return r; }
; template <bool PART, bool SRC16 = false>
; __device__ __forceinline__ void normmod_row2(const void* __restrict__ srcv, const float* __restrict__ g, const float* __restrict__ sh, const float* __restrict__ sc, bf16_t* __restrict__ dst, int lane, const float* __restrict__ bsh = nullptr) {
;     ...
;     else { v[0][i] = __builtin_nontemporal_load((const f32x4*)((const float*)srcv + lane * 4 + 256 * i)); v[1][i] = __builtin_nontemporal_load((const f32x4*)((const float*)srcv + 1024 + lane * 4 + 256 * i)); }
;   }
; #pragma unroll
;   for (int i = 0; i < 4; ++i) {
;     ss0 += v[0][i][0] * v[0][i][0] + v[0][i][1] * v[0][i][1] + v[0][i][2] * v[0][i][2] + v[0][i][3] * v[0][i][3];
;     ss1 += v[1][i][0] * v[1][i][0] + v[1][i][1] * v[1][i][1] + v[1][i][2] * v[1][i][2] + v[1][i][3] * v[1][i][3];
;   }
;   ss0 = wave_sum(ss0); ss1 = wave_sum(ss1);
;   const float r0 = rsqrtf(ss0 * (1.0f / 1024.0f) + 1e-6f), r1 = rsqrtf(ss1 * (1.0f / 1024.0f) + 1e-6f);
; #pragma unroll
;   for (int i = 0; i < 4; ++i) {
;     const int k = lane * 4 + 256 * i;
;     const f32x4 g4 = *(const f32x4*)(g + k);
;     f32x4 s4 = *(const f32x4*)(sh + k), c4 = *(const f32x4*)(sc + k);
;     if (PART) {
; #pragma unroll
;       for (int q = 1; q < 4; ++q) { s4 += *(const f32x4*)(sh + (size_t)q * 110592 + k); c4 += *(const f32x4*)(sc + (size_t)q * 110592 + k); }
;       s4 += *(const f32x4*)(bsh + k); c4 += *(const f32x4*)(bsh + 1024 + k);
;     }
;     float y[4], z[4];
; #pragma unroll
;     for (int j = 0; j < 4; ++j) { const float gm = g4[j] * (1.f + c4[j]); y[j] = (v[0][i][j] * r0) * gm + s4[j]; z[j] = (v[1][i][j] * r1) * gm + s4[j]; }
;     uint2 u; u.x = pack2(y[0], y[1]); u.y = pack2(y[2], y[3]);
;     *(uint2*)(dst + k) = u;
;     u.x = pack2(z[0], z[1]); u.y = pack2(z[2], z[3]);
;     *(uint2*)(dst + 1024 + k) = u;
	v_pk_add_f32 v[56:57], v[124:125], v[128:129]
	v_pk_add_f32 v[56:57], v[56:57], v[132:133]
	v_pk_add_f32 v[56:57], v[56:57], v[136:137]
	v_pk_add_f32 v[40:41], v[140:141], v[144:145]
	v_pk_add_f32 v[40:41], v[40:41], v[148:149]
	v_pk_add_f32 v[40:41], v[40:41], v[152:153]
	v_pk_add_f32 v[58:59], v[126:127], v[130:131]
	v_pk_add_f32 v[58:59], v[58:59], v[134:135]
	v_pk_add_f32 v[58:59], v[58:59], v[138:139]
	v_pk_add_f32 v[42:43], v[142:143], v[146:147]
	v_pk_add_f32 v[42:43], v[42:43], v[150:151]
	v_pk_add_f32 v[42:43], v[42:43], v[154:155]
	v_add_f32_e32 v56, v116, v56
	v_add_f32_e32 v40, v120, v40
	v_add_f32_e32 v40, 1.0, v40
	v_mul_f32_e32 v40, v112, v40
	v_add_f32_e32 v57, v117, v57
	v_add_f32_e32 v41, v121, v41
	v_add_f32_e32 v41, 1.0, v41
	v_mul_f32_e32 v41, v113, v41
	v_add_f32_e32 v58, v118, v58
	v_add_f32_e32 v42, v122, v42
	v_add_f32_e32 v42, 1.0, v42
	v_mul_f32_e32 v42, v114, v42
	v_add_f32_e32 v59, v119, v59
	v_add_f32_e32 v43, v123, v43
	v_add_f32_e32 v43, 1.0, v43
	v_mul_f32_e32 v43, v115, v43
	v_pk_add_f32 v[60:61], v[168:169], v[172:173]
	v_pk_add_f32 v[60:61], v[60:61], v[176:177]
	v_pk_add_f32 v[60:61], v[60:61], v[180:181]
	v_pk_add_f32 v[44:45], v[184:185], v[188:189]
	v_pk_add_f32 v[44:45], v[44:45], v[192:193]
	v_pk_add_f32 v[44:45], v[44:45], v[196:197]
	v_pk_add_f32 v[62:63], v[170:171], v[174:175]
	v_pk_add_f32 v[62:63], v[62:63], v[178:179]
	v_pk_add_f32 v[62:63], v[62:63], v[182:183]
	v_pk_add_f32 v[46:47], v[186:187], v[190:191]
	v_pk_add_f32 v[46:47], v[46:47], v[194:195]
	v_pk_add_f32 v[46:47], v[46:47], v[198:199]
	v_add_f32_e32 v60, v160, v60
	v_add_f32_e32 v44, v164, v44
	v_add_f32_e32 v44, 1.0, v44
	v_mul_f32_e32 v44, v156, v44
	v_add_f32_e32 v61, v161, v61
	v_add_f32_e32 v45, v165, v45
	v_add_f32_e32 v45, 1.0, v45
	v_mul_f32_e32 v45, v157, v45
	v_add_f32_e32 v62, v162, v62
	v_add_f32_e32 v46, v166, v46
	v_add_f32_e32 v46, 1.0, v46
	v_mul_f32_e32 v46, v158, v46
	v_add_f32_e32 v63, v163, v63
	v_add_f32_e32 v47, v167, v47
	v_add_f32_e32 v47, 1.0, v47
	v_mul_f32_e32 v47, v159, v47
	global_load_dwordx4 v[96:99], v3, s[24:25] nt
	global_load_dwordx4 v[100:103], v3, s[24:25] offset:1024 nt
	global_load_dwordx4 v[104:107], v3, s[24:25] offset:2048 nt
	global_load_dwordx4 v[108:111], v3, s[24:25] offset:3072 nt
	s_add_u32 s24, s24, 0x1000
	s_addc_u32 s25, s25, 0
	s_waitcnt vmcnt(8)
	v_mul_f32_e32 v200, v65, v65
	v_mul_f32_e32 v201, v69, v69
	v_mul_f32_e32 v202, v73, v73
	v_mul_f32_e32 v203, v77, v77
	v_fma_f32 v200, v64, v64, v200
	v_fma_f32 v201, v68, v68, v201
	v_fma_f32 v202, v72, v72, v202
	v_fma_f32 v203, v76, v76, v203
	v_fma_f32 v200, v66, v66, v200
	v_fma_f32 v201, v70, v70, v201
	v_fma_f32 v202, v74, v74, v202
	v_fma_f32 v203, v78, v78, v203
	v_fma_f32 v200, v67, v67, v200
	v_fma_f32 v201, v71, v71, v201
	v_fma_f32 v202, v75, v75, v202
	v_fma_f32 v203, v79, v79, v203
	v_add_f32_e32 v204, v200, v201
	v_add_f32_e32 v204, v204, v202
	v_add_f32_e32 v204, v204, v203
	v_mov_b32_e32 v205, v204
	s_nop 1
	v_permlane32_swap_b32 v204, v205
	s_nop 1
	v_add_f32_e32 v204, v204, v205
	v_mov_b32_e32 v205, v204
	s_nop 1
	v_permlane16_swap_b32 v204, v205
	s_nop 1
	v_add_f32_e32 v204, v204, v205
	s_nop 1
	v_add_f32_dpp v204, v204, v204 row_ror:8 row_mask:0xf bank_mask:0xf
	s_nop 1
	v_add_f32_dpp v204, v204, v204 row_ror:4 row_mask:0xf bank_mask:0xf
	s_nop 1
	v_add_f32_dpp v204, v204, v204 row_ror:2 row_mask:0xf bank_mask:0xf
	s_nop 1
	v_add_f32_dpp v204, v204, v204 row_ror:1 row_mask:0xf bank_mask:0xf
	s_nop 1
	v_fma_f32 v206, v204, v211, v210
	v_mul_f32_e32 v207, 0x4b800000, v206
	v_cmp_gt_f32_e32 vcc, 0x800000, v206
	s_nop 1
	v_cndmask_b32_e32 v207, v206, v207, vcc
	v_rsq_f32_e32 v208, v207
	s_nop 1
	v_mul_f32_e32 v207, 0x45800000, v208
	v_cndmask_b32_e32 v208, v208, v207, vcc
	v_mul_f32_e32 v64, v64, v208
	v_mul_f32_e32 v65, v65, v208
	v_mul_f32_e32 v66, v66, v208
	v_mul_f32_e32 v67, v67, v208
	v_fma_f32 v64, v64, v32, v48
	v_fma_f32 v65, v65, v33, v49
	v_fma_f32 v66, v66, v34, v50
	v_fma_f32 v67, v67, v35, v51
	v_cvt_pk_bf16_f32 v64, v64, v65
	v_cvt_pk_bf16_f32 v65, v66, v67
	s_nop 0
	global_store_dwordx2 v4, v[64:65], s[26:27]
	v_mul_f32_e32 v68, v68, v208
	v_mul_f32_e32 v69, v69, v208
	v_mul_f32_e32 v70, v70, v208
	v_mul_f32_e32 v71, v71, v208
	v_fma_f32 v68, v68, v36, v52
	v_fma_f32 v69, v69, v37, v53
	v_fma_f32 v70, v70, v38, v54
	v_fma_f32 v71, v71, v39, v55
	v_cvt_pk_bf16_f32 v68, v68, v69
	v_cvt_pk_bf16_f32 v69, v70, v71
	s_nop 0
	global_store_dwordx2 v4, v[68:69], s[26:27] offset:512
	v_mul_f32_e32 v72, v72, v208
	v_mul_f32_e32 v73, v73, v208
	v_mul_f32_e32 v74, v74, v208
	v_mul_f32_e32 v75, v75, v208
	v_fma_f32 v72, v72, v40, v56
	v_fma_f32 v73, v73, v41, v57
	v_fma_f32 v74, v74, v42, v58
	v_fma_f32 v75, v75, v43, v59
	v_cvt_pk_bf16_f32 v72, v72, v73
	v_cvt_pk_bf16_f32 v73, v74, v75
	s_nop 0
	global_store_dwordx2 v4, v[72:73], s[26:27] offset:1024
	v_mul_f32_e32 v76, v76, v208
	v_mul_f32_e32 v77, v77, v208
	v_mul_f32_e32 v78, v78, v208
	v_mul_f32_e32 v79, v79, v208
	v_fma_f32 v76, v76, v44, v60
	v_fma_f32 v77, v77, v45, v61
	v_fma_f32 v78, v78, v46, v62
	v_fma_f32 v79, v79, v47, v63
	v_cvt_pk_bf16_f32 v76, v76, v77
	v_cvt_pk_bf16_f32 v77, v78, v79
	s_nop 0
	global_store_dwordx2 v4, v[76:77], s[26:27] offset:1536
	s_add_u32 s26, s26, 0x800
	s_addc_u32 s27, s27, 0
	global_load_dwordx4 v[64:67], v3, s[24:25] nt
	global_load_dwordx4 v[68:71], v3, s[24:25] offset:1024 nt
	global_load_dwordx4 v[72:75], v3, s[24:25] offset:2048 nt
	global_load_dwordx4 v[76:79], v3, s[24:25] offset:3072 nt
	s_add_u32 s24, s24, 0x1000
	s_addc_u32 s25, s25, 0
	s_waitcnt vmcnt(12)
; __device__ __forceinline__ unsigned pack2(float a, float b) { unsigned r; asm("v_cvt_pk_bf16_f32 %0, %1, %2" : "=v"(r) : "v"(a), "v"(b)); return r; }
; template <bool PART, bool SRC16 = false>
; __device__ __forceinline__ void normmod_row2(const void* __restrict__ srcv, const float* __restrict__ g, const float* __restrict__ sh, const float* __restrict__ sc, bf16_t* __restrict__ dst, int lane, const float* __restrict__ bsh = nullptr) {
;     ...
;     else { v[0][i] = __builtin_nontemporal_load((const f32x4*)((const float*)srcv + lane * 4 + 256 * i)); v[1][i] = __builtin_nontemporal_load((const f32x4*)((const float*)srcv + 1024 + lane * 4 + 256 * i)); }
;   }
; #pragma unroll
;   for (int i = 0; i < 4; ++i) {
;     ss0 += v[0][i][0] * v[0][i][0] + v[0][i][1] * v[0][i][1] + v[0][i][2] * v[0][i][2] + v[0][i][3] * v[0][i][3];
;     ss1 += v[1][i][0] * v[1][i][0] + v[1][i][1] * v[1][i][1] + v[1][i][2] * v[1][i][2] + v[1][i][3] * v[1][i][3];
;   }
;   ss0 = wave_sum(ss0); ss1 = wave_sum(ss1);
;   const float r0 = rsqrtf(ss0 * (1.0f / 1024.0f) + 1e-6f), r1 = rsqrtf(ss1 * (1.0f / 1024.0f) + 1e-6f);
; #pragma unroll
;   for (int i = 0; i < 4; ++i) {
;     const int k = lane * 4 + 256 * i;
;     const f32x4 g4 = *(const f32x4*)(g + k);
;     f32x4 s4 = *(const f32x4*)(sh + k), c4 = *(const f32x4*)(sc + k);
;     if (PART) {
; #pragma unroll
;       for (int q = 1; q < 4; ++q) { s4 += *(const f32x4*)(sh + (size_t)q * 110592 + k); c4 += *(const f32x4*)(sc + (size_t)q * 110592 + k); }
;       s4 += *(const f32x4*)(bsh + k); c4 += *(const f32x4*)(bsh + 1024 + k);
;     }
;     float y[4], z[4];
; #pragma unroll
;     for (int j = 0; j < 4; ++j) { const float gm = g4[j] * (1.f + c4[j]); y[j] = (v[0][i][j] * r0) * gm + s4[j]; z[j] = (v[1][i][j] * r1) * gm + s4[j]; }
;     uint2 u; u.x = pack2(y[0], y[1]); u.y = pack2(y[2], y[3]);
;     *(uint2*)(dst + k) = u;
;     u.x = pack2(z[0], z[1]); u.y = pack2(z[2], z[3]);
;     *(uint2*)(dst + 1024 + k) = u;
	v_mul_f32_e32 v200, v81, v81
	v_mul_f32_e32 v201, v85, v85
	v_mul_f32_e32 v202, v89, v89
	v_mul_f32_e32 v203, v93, v93
	v_fma_f32 v200, v80, v80, v200
	v_fma_f32 v201, v84, v84, v201
	v_fma_f32 v202, v88, v88, v202
	v_fma_f32 v203, v92, v92, v203
	v_fma_f32 v200, v82, v82, v200
	v_fma_f32 v201, v86, v86, v201
	v_fma_f32 v202, v90, v90, v202
	v_fma_f32 v203, v94, v94, v203
	v_fma_f32 v200, v83, v83, v200
	v_fma_f32 v201, v87, v87, v201
	v_fma_f32 v202, v91, v91, v202
	v_fma_f32 v203, v95, v95, v203
	v_add_f32_e32 v204, v200, v201
	v_add_f32_e32 v204, v204, v202
	v_add_f32_e32 v204, v204, v203
	v_mov_b32_e32 v205, v204
	s_nop 1
	v_permlane32_swap_b32 v204, v205
	s_nop 1
	v_add_f32_e32 v204, v204, v205
	v_mov_b32_e32 v205, v204
	s_nop 1
	v_permlane16_swap_b32 v204, v205
	s_nop 1
	v_add_f32_e32 v204, v204, v205
	s_nop 1
	v_add_f32_dpp v204, v204, v204 row_ror:8 row_mask:0xf bank_mask:0xf
	s_nop 1
	v_add_f32_dpp v204, v204, v204 row_ror:4 row_mask:0xf bank_mask:0xf
	s_nop 1
	v_add_f32_dpp v204, v204, v204 row_ror:2 row_mask:0xf bank_mask:0xf
	s_nop 1
	v_add_f32_dpp v204, v204, v204 row_ror:1 row_mask:0xf bank_mask:0xf
	s_nop 1
	v_fma_f32 v206, v204, v211, v210
	v_mul_f32_e32 v207, 0x4b800000, v206
	v_cmp_gt_f32_e32 vcc, 0x800000, v206
	s_nop 1
	v_cndmask_b32_e32 v207, v206, v207, vcc
	v_rsq_f32_e32 v208, v207
	s_nop 1
	v_mul_f32_e32 v207, 0x45800000, v208
	v_cndmask_b32_e32 v208, v208, v207, vcc
	v_mul_f32_e32 v80, v80, v208
	v_mul_f32_e32 v81, v81, v208
	v_mul_f32_e32 v82, v82, v208
	v_mul_f32_e32 v83, v83, v208
	v_fma_f32 v80, v80, v32, v48
	v_fma_f32 v81, v81, v33, v49
	v_fma_f32 v82, v82, v34, v50
	v_fma_f32 v83, v83, v35, v51
	v_cvt_pk_bf16_f32 v80, v80, v81
	v_cvt_pk_bf16_f32 v81, v82, v83
	s_nop 0
	global_store_dwordx2 v4, v[80:81], s[26:27]
	v_mul_f32_e32 v84, v84, v208
	v_mul_f32_e32 v85, v85, v208
	v_mul_f32_e32 v86, v86, v208
	v_mul_f32_e32 v87, v87, v208
	v_fma_f32 v84, v84, v36, v52
	v_fma_f32 v85, v85, v37, v53
	v_fma_f32 v86, v86, v38, v54
	v_fma_f32 v87, v87, v39, v55
	v_cvt_pk_bf16_f32 v84, v84, v85
	v_cvt_pk_bf16_f32 v85, v86, v87
	s_nop 0
	global_store_dwordx2 v4, v[84:85], s[26:27] offset:512
	v_mul_f32_e32 v88, v88, v208
	v_mul_f32_e32 v89, v89, v208
	v_mul_f32_e32 v90, v90, v208
	v_mul_f32_e32 v91, v91, v208
	v_fma_f32 v88, v88, v40, v56
	v_fma_f32 v89, v89, v41, v57
	v_fma_f32 v90, v90, v42, v58
	v_fma_f32 v91, v91, v43, v59
	v_cvt_pk_bf16_f32 v88, v88, v89
	v_cvt_pk_bf16_f32 v89, v90, v91
	s_nop 0
	global_store_dwordx2 v4, v[88:89], s[26:27] offset:1024
	v_mul_f32_e32 v92, v92, v208
	v_mul_f32_e32 v93, v93, v208
	v_mul_f32_e32 v94, v94, v208
	v_mul_f32_e32 v95, v95, v208
	v_fma_f32 v92, v92, v44, v60
	v_fma_f32 v93, v93, v45, v61
	v_fma_f32 v94, v94, v46, v62
	v_fma_f32 v95, v95, v47, v63
	v_cvt_pk_bf16_f32 v92, v92, v93
	v_cvt_pk_bf16_f32 v93, v94, v95
	s_nop 0
	global_store_dwordx2 v4, v[92:93], s[26:27] offset:1536
	s_add_u32 s26, s26, 0x800
	s_addc_u32 s27, s27, 0
	global_load_dwordx4 v[80:83], v3, s[24:25] nt
	global_load_dwordx4 v[84:87], v3, s[24:25] offset:1024 nt
	global_load_dwordx4 v[88:91], v3, s[24:25] offset:2048 nt
	global_load_dwordx4 v[92:95], v3, s[24:25] offset:3072 nt
	s_add_u32 s24, s24, 0x1000
	s_addc_u32 s25, s25, 0
	s_waitcnt vmcnt(16)
	v_mul_f32_e32 v200, v97, v97
	v_mul_f32_e32 v201, v101, v101
	v_mul_f32_e32 v202, v105, v105
	v_mul_f32_e32 v203, v109, v109
	v_fma_f32 v200, v96, v96, v200
	v_fma_f32 v201, v100, v100, v201
	v_fma_f32 v202, v104, v104, v202
	v_fma_f32 v203, v108, v108, v203
	v_fma_f32 v200, v98, v98, v200
	v_fma_f32 v201, v102, v102, v201
	v_fma_f32 v202, v106, v106, v202
	v_fma_f32 v203, v110, v110, v203
	v_fma_f32 v200, v99, v99, v200
	v_fma_f32 v201, v103, v103, v201
	v_fma_f32 v202, v107, v107, v202
	v_fma_f32 v203, v111, v111, v203
	v_add_f32_e32 v204, v200, v201
	v_add_f32_e32 v204, v204, v202
	v_add_f32_e32 v204, v204, v203
	v_mov_b32_e32 v205, v204
	s_nop 1
	v_permlane32_swap_b32 v204, v205
	s_nop 1
	v_add_f32_e32 v204, v204, v205
	v_mov_b32_e32 v205, v204
	s_nop 1
	v_permlane16_swap_b32 v204, v205
	s_nop 1
	v_add_f32_e32 v204, v204, v205
	s_nop 1
	v_add_f32_dpp v204, v204, v204 row_ror:8 row_mask:0xf bank_mask:0xf
	s_nop 1
	v_add_f32_dpp v204, v204, v204 row_ror:4 row_mask:0xf bank_mask:0xf
	s_nop 1
	v_add_f32_dpp v204, v204, v204 row_ror:2 row_mask:0xf bank_mask:0xf
	s_nop 1
	v_add_f32_dpp v204, v204, v204 row_ror:1 row_mask:0xf bank_mask:0xf
	s_nop 1
	v_fma_f32 v206, v204, v211, v210
	v_mul_f32_e32 v207, 0x4b800000, v206
	v_cmp_gt_f32_e32 vcc, 0x800000, v206
	s_nop 1
	v_cndmask_b32_e32 v207, v206, v207, vcc
	v_rsq_f32_e32 v208, v207
	s_nop 1
	v_mul_f32_e32 v207, 0x45800000, v208
	v_cndmask_b32_e32 v208, v208, v207, vcc
	v_mul_f32_e32 v96, v96, v208
	v_mul_f32_e32 v97, v97, v208
	v_mul_f32_e32 v98, v98, v208
	v_mul_f32_e32 v99, v99, v208
	v_fma_f32 v96, v96, v32, v48
	v_fma_f32 v97, v97, v33, v49
	v_fma_f32 v98, v98, v34, v50
	v_fma_f32 v99, v99, v35, v51
	v_cvt_pk_bf16_f32 v96, v96, v97
	v_cvt_pk_bf16_f32 v97, v98, v99
	s_nop 0
	global_store_dwordx2 v4, v[96:97], s[26:27]
	v_mul_f32_e32 v100, v100, v208
	v_mul_f32_e32 v101, v101, v208
	v_mul_f32_e32 v102, v102, v208
	v_mul_f32_e32 v103, v103, v208
	v_fma_f32 v100, v100, v36, v52
	v_fma_f32 v101, v101, v37, v53
	v_fma_f32 v102, v102, v38, v54
	v_fma_f32 v103, v103, v39, v55
	v_cvt_pk_bf16_f32 v100, v100, v101
	v_cvt_pk_bf16_f32 v101, v102, v103
	s_nop 0
	global_store_dwordx2 v4, v[100:101], s[26:27] offset:512
	v_mul_f32_e32 v104, v104, v208
	v_mul_f32_e32 v105, v105, v208
	v_mul_f32_e32 v106, v106, v208
	v_mul_f32_e32 v107, v107, v208
	v_fma_f32 v104, v104, v40, v56
	v_fma_f32 v105, v105, v41, v57
	v_fma_f32 v106, v106, v42, v58
	v_fma_f32 v107, v107, v43, v59
	v_cvt_pk_bf16_f32 v104, v104, v105
	v_cvt_pk_bf16_f32 v105, v106, v107
	s_nop 0
	global_store_dwordx2 v4, v[104:105], s[26:27] offset:1024
	v_mul_f32_e32 v108, v108, v208
	v_mul_f32_e32 v109, v109, v208
	v_mul_f32_e32 v110, v110, v208
	v_mul_f32_e32 v111, v111, v208
	v_fma_f32 v108, v108, v44, v60
	v_fma_f32 v109, v109, v45, v61
	v_fma_f32 v110, v110, v46, v62
	v_fma_f32 v111, v111, v47, v63
	v_cvt_pk_bf16_f32 v108, v108, v109
	v_cvt_pk_bf16_f32 v109, v110, v111
	s_nop 0
	global_store_dwordx2 v4, v[108:109], s[26:27] offset:1536
	s_add_u32 s26, s26, 0x800
	s_addc_u32 s27, s27, 0
	global_load_dwordx4 v[96:99], v3, s[24:25] nt
	global_load_dwordx4 v[100:103], v3, s[24:25] offset:1024 nt
	global_load_dwordx4 v[104:107], v3, s[24:25] offset:2048 nt
	global_load_dwordx4 v[108:111], v3, s[24:25] offset:3072 nt
	s_add_u32 s24, s24, 0x1000
	s_addc_u32 s25, s25, 0
	s_waitcnt vmcnt(16)
; __device__ __forceinline__ unsigned pack2(float a, float b) { unsigned r; asm("v_cvt_pk_bf16_f32 %0, %1, %2" : "=v"(r) : "v"(a), "v"(b)); return r; }
; template <bool PART, bool SRC16 = false>
; __device__ __forceinline__ void normmod_row2(const void* __restrict__ srcv, const float* __restrict__ g, const float* __restrict__ sh, const float* __restrict__ sc, bf16_t* __restrict__ dst, int lane, const float* __restrict__ bsh = nullptr) {
;     ...
;     else { v[0][i] = __builtin_nontemporal_load((const f32x4*)((const float*)srcv + lane * 4 + 256 * i)); v[1][i] = __builtin_nontemporal_load((const f32x4*)((const float*)srcv + 1024 + lane * 4 + 256 * i)); }
;   }
; #pragma unroll
;   for (int i = 0; i < 4; ++i) {
;     ss0 += v[0][i][0] * v[0][i][0] + v[0][i][1] * v[0][i][1] + v[0][i][2] * v[0][i][2] + v[0][i][3] * v[0][i][3];
;     ss1 += v[1][i][0] * v[1][i][0] + v[1][i][1] * v[1][i][1] + v[1][i][2] * v[1][i][2] + v[1][i][3] * v[1][i][3];
;   }
;   ss0 = wave_sum(ss0); ss1 = wave_sum(ss1);
;   const float r0 = rsqrtf(ss0 * (1.0f / 1024.0f) + 1e-6f), r1 = rsqrtf(ss1 * (1.0f / 1024.0f) + 1e-6f);
; #pragma unroll
;   for (int i = 0; i < 4; ++i) {
;     const int k = lane * 4 + 256 * i;
;     const f32x4 g4 = *(const f32x4*)(g + k);
;     f32x4 s4 = *(const f32x4*)(sh + k), c4 = *(const f32x4*)(sc + k);
;     if (PART) {
; #pragma unroll
;       for (int q = 1; q < 4; ++q) { s4 += *(const f32x4*)(sh + (size_t)q * 110592 + k); c4 += *(const f32x4*)(sc + (size_t)q * 110592 + k); }
;       s4 += *(const f32x4*)(bsh + k); c4 += *(const f32x4*)(bsh + 1024 + k);
;     }
;     float y[4], z[4];
; #pragma unroll
;     for (int j = 0; j < 4; ++j) { const float gm = g4[j] * (1.f + c4[j]); y[j] = (v[0][i][j] * r0) * gm + s4[j]; z[j] = (v[1][i][j] * r1) * gm + s4[j]; }
;     uint2 u; u.x = pack2(y[0], y[1]); u.y = pack2(y[2], y[3]);
;     *(uint2*)(dst + k) = u;
;     u.x = pack2(z[0], z[1]); u.y = pack2(z[2], z[3]);
;     *(uint2*)(dst + 1024 + k) = u;
	v_mul_f32_e32 v200, v65, v65
	v_mul_f32_e32 v201, v69, v69
	v_mul_f32_e32 v202, v73, v73
	v_mul_f32_e32 v203, v77, v77
	v_fma_f32 v200, v64, v64, v200
	v_fma_f32 v201, v68, v68, v201
	v_fma_f32 v202, v72, v72, v202
	v_fma_f32 v203, v76, v76, v203
	v_fma_f32 v200, v66, v66, v200
	v_fma_f32 v201, v70, v70, v201
	v_fma_f32 v202, v74, v74, v202
	v_fma_f32 v203, v78, v78, v203
	v_fma_f32 v200, v67, v67, v200
	v_fma_f32 v201, v71, v71, v201
	v_fma_f32 v202, v75, v75, v202
	v_fma_f32 v203, v79, v79, v203
	v_add_f32_e32 v204, v200, v201
	v_add_f32_e32 v204, v204, v202
	v_add_f32_e32 v204, v204, v203
	v_mov_b32_e32 v205, v204
	s_nop 1
	v_permlane32_swap_b32 v204, v205
	s_nop 1
	v_add_f32_e32 v204, v204, v205
	v_mov_b32_e32 v205, v204
	s_nop 1
	v_permlane16_swap_b32 v204, v205
	s_nop 1
	v_add_f32_e32 v204, v204, v205
	s_nop 1
	v_add_f32_dpp v204, v204, v204 row_ror:8 row_mask:0xf bank_mask:0xf
	s_nop 1
	v_add_f32_dpp v204, v204, v204 row_ror:4 row_mask:0xf bank_mask:0xf
	s_nop 1
	v_add_f32_dpp v204, v204, v204 row_ror:2 row_mask:0xf bank_mask:0xf
	s_nop 1
	v_add_f32_dpp v204, v204, v204 row_ror:1 row_mask:0xf bank_mask:0xf
	s_nop 1
	v_fma_f32 v206, v204, v211, v210
	v_mul_f32_e32 v207, 0x4b800000, v206
	v_cmp_gt_f32_e32 vcc, 0x800000, v206
	s_nop 1
	v_cndmask_b32_e32 v207, v206, v207, vcc
	v_rsq_f32_e32 v208, v207
	s_nop 1
	v_mul_f32_e32 v207, 0x45800000, v208
	v_cndmask_b32_e32 v208, v208, v207, vcc
	v_mul_f32_e32 v64, v64, v208
	v_mul_f32_e32 v65, v65, v208
	v_mul_f32_e32 v66, v66, v208
	v_mul_f32_e32 v67, v67, v208
	v_fma_f32 v64, v64, v32, v48
	v_fma_f32 v65, v65, v33, v49
	v_fma_f32 v66, v66, v34, v50
	v_fma_f32 v67, v67, v35, v51
	v_cvt_pk_bf16_f32 v64, v64, v65
	v_cvt_pk_bf16_f32 v65, v66, v67
	s_nop 0
	global_store_dwordx2 v4, v[64:65], s[26:27]
	v_mul_f32_e32 v68, v68, v208
	v_mul_f32_e32 v69, v69, v208
	v_mul_f32_e32 v70, v70, v208
	v_mul_f32_e32 v71, v71, v208
	v_fma_f32 v68, v68, v36, v52
	v_fma_f32 v69, v69, v37, v53
	v_fma_f32 v70, v70, v38, v54
	v_fma_f32 v71, v71, v39, v55
	v_cvt_pk_bf16_f32 v68, v68, v69
	v_cvt_pk_bf16_f32 v69, v70, v71
	s_nop 0
	global_store_dwordx2 v4, v[68:69], s[26:27] offset:512
	v_mul_f32_e32 v72, v72, v208
	v_mul_f32_e32 v73, v73, v208
	v_mul_f32_e32 v74, v74, v208
	v_mul_f32_e32 v75, v75, v208
	v_fma_f32 v72, v72, v40, v56
	v_fma_f32 v73, v73, v41, v57
	v_fma_f32 v74, v74, v42, v58
	v_fma_f32 v75, v75, v43, v59
	v_cvt_pk_bf16_f32 v72, v72, v73
	v_cvt_pk_bf16_f32 v73, v74, v75
	s_nop 0
	global_store_dwordx2 v4, v[72:73], s[26:27] offset:1024
	v_mul_f32_e32 v76, v76, v208
	v_mul_f32_e32 v77, v77, v208
	v_mul_f32_e32 v78, v78, v208
	v_mul_f32_e32 v79, v79, v208
	v_fma_f32 v76, v76, v44, v60
	v_fma_f32 v77, v77, v45, v61
	v_fma_f32 v78, v78, v46, v62
	v_fma_f32 v79, v79, v47, v63
	v_cvt_pk_bf16_f32 v76, v76, v77
	v_cvt_pk_bf16_f32 v77, v78, v79
	s_nop 0
	global_store_dwordx2 v4, v[76:77], s[26:27] offset:1536
	s_add_u32 s26, s26, 0x800
	s_addc_u32 s27, s27, 0
	global_load_dwordx4 v[64:67], v3, s[24:25] nt
	global_load_dwordx4 v[68:71], v3, s[24:25] offset:1024 nt
	global_load_dwordx4 v[72:75], v3, s[24:25] offset:2048 nt
	global_load_dwordx4 v[76:79], v3, s[24:25] offset:3072 nt
	s_add_u32 s24, s24, 0x1000
	s_addc_u32 s25, s25, 0
	s_waitcnt vmcnt(16)
	v_mul_f32_e32 v200, v81, v81
	v_mul_f32_e32 v201, v85, v85
	v_mul_f32_e32 v202, v89, v89
	v_mul_f32_e32 v203, v93, v93
	v_fma_f32 v200, v80, v80, v200
	v_fma_f32 v201, v84, v84, v201
	v_fma_f32 v202, v88, v88, v202
	v_fma_f32 v203, v92, v92, v203
	v_fma_f32 v200, v82, v82, v200
	v_fma_f32 v201, v86, v86, v201
	v_fma_f32 v202, v90, v90, v202
	v_fma_f32 v203, v94, v94, v203
	v_fma_f32 v200, v83, v83, v200
	v_fma_f32 v201, v87, v87, v201
	v_fma_f32 v202, v91, v91, v202
	v_fma_f32 v203, v95, v95, v203
	v_add_f32_e32 v204, v200, v201
	v_add_f32_e32 v204, v204, v202
	v_add_f32_e32 v204, v204, v203
	v_mov_b32_e32 v205, v204
	s_nop 1
	v_permlane32_swap_b32 v204, v205
	s_nop 1
	v_add_f32_e32 v204, v204, v205
	v_mov_b32_e32 v205, v204
	s_nop 1
	v_permlane16_swap_b32 v204, v205
	s_nop 1
	v_add_f32_e32 v204, v204, v205
	s_nop 1
	v_add_f32_dpp v204, v204, v204 row_ror:8 row_mask:0xf bank_mask:0xf
	s_nop 1
	v_add_f32_dpp v204, v204, v204 row_ror:4 row_mask:0xf bank_mask:0xf
	s_nop 1
	v_add_f32_dpp v204, v204, v204 row_ror:2 row_mask:0xf bank_mask:0xf
	s_nop 1
	v_add_f32_dpp v204, v204, v204 row_ror:1 row_mask:0xf bank_mask:0xf
	s_nop 1
	v_fma_f32 v206, v204, v211, v210
	v_mul_f32_e32 v207, 0x4b800000, v206
	v_cmp_gt_f32_e32 vcc, 0x800000, v206
	s_nop 1
	v_cndmask_b32_e32 v207, v206, v207, vcc
	v_rsq_f32_e32 v208, v207
	s_nop 1
	v_mul_f32_e32 v207, 0x45800000, v208
	v_cndmask_b32_e32 v208, v208, v207, vcc
	v_mul_f32_e32 v80, v80, v208
	v_mul_f32_e32 v81, v81, v208
	v_mul_f32_e32 v82, v82, v208
	v_mul_f32_e32 v83, v83, v208
	v_fma_f32 v80, v80, v32, v48
	v_fma_f32 v81, v81, v33, v49
	v_fma_f32 v82, v82, v34, v50
	v_fma_f32 v83, v83, v35, v51
	v_cvt_pk_bf16_f32 v80, v80, v81
	v_cvt_pk_bf16_f32 v81, v82, v83
	s_nop 0
	global_store_dwordx2 v4, v[80:81], s[26:27]
	v_mul_f32_e32 v84, v84, v208
	v_mul_f32_e32 v85, v85, v208
	v_mul_f32_e32 v86, v86, v208
	v_mul_f32_e32 v87, v87, v208
	v_fma_f32 v84, v84, v36, v52
	v_fma_f32 v85, v85, v37, v53
	v_fma_f32 v86, v86, v38, v54
	v_fma_f32 v87, v87, v39, v55
	v_cvt_pk_bf16_f32 v84, v84, v85
	v_cvt_pk_bf16_f32 v85, v86, v87
	s_nop 0
	global_store_dwordx2 v4, v[84:85], s[26:27] offset:512
	v_mul_f32_e32 v88, v88, v208
	v_mul_f32_e32 v89, v89, v208
	v_mul_f32_e32 v90, v90, v208
	v_mul_f32_e32 v91, v91, v208
	v_fma_f32 v88, v88, v40, v56
	v_fma_f32 v89, v89, v41, v57
	v_fma_f32 v90, v90, v42, v58
	v_fma_f32 v91, v91, v43, v59
	v_cvt_pk_bf16_f32 v88, v88, v89
	v_cvt_pk_bf16_f32 v89, v90, v91
	s_nop 0
	global_store_dwordx2 v4, v[88:89], s[26:27] offset:1024
	v_mul_f32_e32 v92, v92, v208
	v_mul_f32_e32 v93, v93, v208
	v_mul_f32_e32 v94, v94, v208
	v_mul_f32_e32 v95, v95, v208
	v_fma_f32 v92, v92, v44, v60
	v_fma_f32 v93, v93, v45, v61
	v_fma_f32 v94, v94, v46, v62
	v_fma_f32 v95, v95, v47, v63
	v_cvt_pk_bf16_f32 v92, v92, v93
	v_cvt_pk_bf16_f32 v93, v94, v95
	s_nop 0
	global_store_dwordx2 v4, v[92:93], s[26:27] offset:1536
	s_add_u32 s26, s26, 0x800
	s_addc_u32 s27, s27, 0
	global_load_dwordx4 v[80:83], v3, s[24:25] nt
	global_load_dwordx4 v[84:87], v3, s[24:25] offset:1024 nt
	global_load_dwordx4 v[88:91], v3, s[24:25] offset:2048 nt
	global_load_dwordx4 v[92:95], v3, s[24:25] offset:3072 nt
	s_add_u32 s24, s24, 0x1000
	s_addc_u32 s25, s25, 0
	s_waitcnt vmcnt(16)
; __device__ __forceinline__ unsigned pack2(float a, float b) { unsigned r; asm("v_cvt_pk_bf16_f32 %0, %1, %2" : "=v"(r) : "v"(a), "v"(b)); return r; }
; template <bool PART, bool SRC16 = false>
; __device__ __forceinline__ void normmod_row2(const void* __restrict__ srcv, const float* __restrict__ g, const float* __restrict__ sh, const float* __restrict__ sc, bf16_t* __restrict__ dst, int lane, const float* __restrict__ bsh = nullptr) {
;     ...
;     else { v[0][i] = __builtin_nontemporal_load((const f32x4*)((const float*)srcv + lane * 4 + 256 * i)); v[1][i] = __builtin_nontemporal_load((const f32x4*)((const float*)srcv + 1024 + lane * 4 + 256 * i)); }
;   }
; #pragma unroll
;   for (int i = 0; i < 4; ++i) {
;     ss0 += v[0][i][0] * v[0][i][0] + v[0][i][1] * v[0][i][1] + v[0][i][2] * v[0][i][2] + v[0][i][3] * v[0][i][3];
;     ss1 += v[1][i][0] * v[1][i][0] + v[1][i][1] * v[1][i][1] + v[1][i][2] * v[1][i][2] + v[1][i][3] * v[1][i][3];
;   }
;   ss0 = wave_sum(ss0); ss1 = wave_sum(ss1);
;   const float r0 = rsqrtf(ss0 * (1.0f / 1024.0f) + 1e-6f), r1 = rsqrtf(ss1 * (1.0f / 1024.0f) + 1e-6f);
; #pragma unroll
;   for (int i = 0; i < 4; ++i) {
;     const int k = lane * 4 + 256 * i;
;     const f32x4 g4 = *(const f32x4*)(g + k);
;     f32x4 s4 = *(const f32x4*)(sh + k), c4 = *(const f32x4*)(sc + k);
;     if (PART) {
; #pragma unroll
;       for (int q = 1; q < 4; ++q) { s4 += *(const f32x4*)(sh + (size_t)q * 110592 + k); c4 += *(const f32x4*)(sc + (size_t)q * 110592 + k); }
;       s4 += *(const f32x4*)(bsh + k); c4 += *(const f32x4*)(bsh + 1024 + k);
;     }
;     float y[4], z[4];
; #pragma unroll
;     for (int j = 0; j < 4; ++j) { const float gm = g4[j] * (1.f + c4[j]); y[j] = (v[0][i][j] * r0) * gm + s4[j]; z[j] = (v[1][i][j] * r1) * gm + s4[j]; }
;     uint2 u; u.x = pack2(y[0], y[1]); u.y = pack2(y[2], y[3]);
;     *(uint2*)(dst + k) = u;
;     u.x = pack2(z[0], z[1]); u.y = pack2(z[2], z[3]);
;     *(uint2*)(dst + 1024 + k) = u;
	v_mul_f32_e32 v200, v97, v97
	v_mul_f32_e32 v201, v101, v101
	v_mul_f32_e32 v202, v105, v105
	v_mul_f32_e32 v203, v109, v109
	v_fma_f32 v200, v96, v96, v200
	v_fma_f32 v201, v100, v100, v201
	v_fma_f32 v202, v104, v104, v202
	v_fma_f32 v203, v108, v108, v203
	v_fma_f32 v200, v98, v98, v200
	v_fma_f32 v201, v102, v102, v201
	v_fma_f32 v202, v106, v106, v202
	v_fma_f32 v203, v110, v110, v203
	v_fma_f32 v200, v99, v99, v200
	v_fma_f32 v201, v103, v103, v201
	v_fma_f32 v202, v107, v107, v202
	v_fma_f32 v203, v111, v111, v203
	v_add_f32_e32 v204, v200, v201
	v_add_f32_e32 v204, v204, v202
	v_add_f32_e32 v204, v204, v203
	v_mov_b32_e32 v205, v204
	s_nop 1
	v_permlane32_swap_b32 v204, v205
	s_nop 1
	v_add_f32_e32 v204, v204, v205
	v_mov_b32_e32 v205, v204
	s_nop 1
	v_permlane16_swap_b32 v204, v205
	s_nop 1
	v_add_f32_e32 v204, v204, v205
	s_nop 1
	v_add_f32_dpp v204, v204, v204 row_ror:8 row_mask:0xf bank_mask:0xf
	s_nop 1
	v_add_f32_dpp v204, v204, v204 row_ror:4 row_mask:0xf bank_mask:0xf
	s_nop 1
	v_add_f32_dpp v204, v204, v204 row_ror:2 row_mask:0xf bank_mask:0xf
	s_nop 1
	v_add_f32_dpp v204, v204, v204 row_ror:1 row_mask:0xf bank_mask:0xf
	s_nop 1
	v_fma_f32 v206, v204, v211, v210
	v_mul_f32_e32 v207, 0x4b800000, v206
	v_cmp_gt_f32_e32 vcc, 0x800000, v206
	s_nop 1
	v_cndmask_b32_e32 v207, v206, v207, vcc
	v_rsq_f32_e32 v208, v207
	s_nop 1
	v_mul_f32_e32 v207, 0x45800000, v208
	v_cndmask_b32_e32 v208, v208, v207, vcc
	v_mul_f32_e32 v96, v96, v208
	v_mul_f32_e32 v97, v97, v208
	v_mul_f32_e32 v98, v98, v208
	v_mul_f32_e32 v99, v99, v208
	v_fma_f32 v96, v96, v32, v48
	v_fma_f32 v97, v97, v33, v49
	v_fma_f32 v98, v98, v34, v50
	v_fma_f32 v99, v99, v35, v51
	v_cvt_pk_bf16_f32 v96, v96, v97
	v_cvt_pk_bf16_f32 v97, v98, v99
	s_nop 0
	global_store_dwordx2 v4, v[96:97], s[26:27]
	v_mul_f32_e32 v100, v100, v208
	v_mul_f32_e32 v101, v101, v208
	v_mul_f32_e32 v102, v102, v208
	v_mul_f32_e32 v103, v103, v208
	v_fma_f32 v100, v100, v36, v52
	v_fma_f32 v101, v101, v37, v53
	v_fma_f32 v102, v102, v38, v54
	v_fma_f32 v103, v103, v39, v55
	v_cvt_pk_bf16_f32 v100, v100, v101
	v_cvt_pk_bf16_f32 v101, v102, v103
	s_nop 0
	global_store_dwordx2 v4, v[100:101], s[26:27] offset:512
	v_mul_f32_e32 v104, v104, v208
	v_mul_f32_e32 v105, v105, v208
	v_mul_f32_e32 v106, v106, v208
	v_mul_f32_e32 v107, v107, v208
	v_fma_f32 v104, v104, v40, v56
	v_fma_f32 v105, v105, v41, v57
	v_fma_f32 v106, v106, v42, v58
	v_fma_f32 v107, v107, v43, v59
	v_cvt_pk_bf16_f32 v104, v104, v105
	v_cvt_pk_bf16_f32 v105, v106, v107
	s_nop 0
	global_store_dwordx2 v4, v[104:105], s[26:27] offset:1024
	v_mul_f32_e32 v108, v108, v208
	v_mul_f32_e32 v109, v109, v208
	v_mul_f32_e32 v110, v110, v208
	v_mul_f32_e32 v111, v111, v208
	v_fma_f32 v108, v108, v44, v60
	v_fma_f32 v109, v109, v45, v61
	v_fma_f32 v110, v110, v46, v62
	v_fma_f32 v111, v111, v47, v63
	v_cvt_pk_bf16_f32 v108, v108, v109
	v_cvt_pk_bf16_f32 v109, v110, v111
	s_nop 0
	global_store_dwordx2 v4, v[108:109], s[26:27] offset:1536
	s_add_u32 s26, s26, 0x800
	s_addc_u32 s27, s27, 0
	global_load_dwordx4 v[96:99], v3, s[20:21] nt
	global_load_dwordx4 v[100:103], v3, s[20:21] offset:1024 nt
	global_load_dwordx4 v[104:107], v3, s[20:21] offset:2048 nt
	global_load_dwordx4 v[108:111], v3, s[20:21] offset:3072 nt
	s_waitcnt vmcnt(16)
	v_mul_f32_e32 v200, v65, v65
	v_mul_f32_e32 v201, v69, v69
	v_mul_f32_e32 v202, v73, v73
	v_mul_f32_e32 v203, v77, v77
	v_fma_f32 v200, v64, v64, v200
	v_fma_f32 v201, v68, v68, v201
	v_fma_f32 v202, v72, v72, v202
	v_fma_f32 v203, v76, v76, v203
	v_fma_f32 v200, v66, v66, v200
	v_fma_f32 v201, v70, v70, v201
	v_fma_f32 v202, v74, v74, v202
	v_fma_f32 v203, v78, v78, v203
	v_fma_f32 v200, v67, v67, v200
	v_fma_f32 v201, v71, v71, v201
	v_fma_f32 v202, v75, v75, v202
	v_fma_f32 v203, v79, v79, v203
	v_add_f32_e32 v204, v200, v201
	v_add_f32_e32 v204, v204, v202
	v_add_f32_e32 v204, v204, v203
	v_mov_b32_e32 v205, v204
	s_nop 1
	v_permlane32_swap_b32 v204, v205
	s_nop 1
	v_add_f32_e32 v204, v204, v205
	v_mov_b32_e32 v205, v204
	s_nop 1
	v_permlane16_swap_b32 v204, v205
	s_nop 1
	v_add_f32_e32 v204, v204, v205
	s_nop 1
	v_add_f32_dpp v204, v204, v204 row_ror:8 row_mask:0xf bank_mask:0xf
	s_nop 1
	v_add_f32_dpp v204, v204, v204 row_ror:4 row_mask:0xf bank_mask:0xf
	s_nop 1
	v_add_f32_dpp v204, v204, v204 row_ror:2 row_mask:0xf bank_mask:0xf
	s_nop 1
	v_add_f32_dpp v204, v204, v204 row_ror:1 row_mask:0xf bank_mask:0xf
	s_nop 1
	v_fma_f32 v206, v204, v211, v210
	v_mul_f32_e32 v207, 0x4b800000, v206
	v_cmp_gt_f32_e32 vcc, 0x800000, v206
	s_nop 1
	v_cndmask_b32_e32 v207, v206, v207, vcc
	v_rsq_f32_e32 v208, v207
	s_nop 1
	v_mul_f32_e32 v207, 0x45800000, v208
	v_cndmask_b32_e32 v208, v208, v207, vcc
	v_mul_f32_e32 v64, v64, v208
	v_mul_f32_e32 v65, v65, v208
	v_mul_f32_e32 v66, v66, v208
	v_mul_f32_e32 v67, v67, v208
	v_fma_f32 v64, v64, v32, v48
	v_fma_f32 v65, v65, v33, v49
	v_fma_f32 v66, v66, v34, v50
	v_fma_f32 v67, v67, v35, v51
	v_cvt_pk_bf16_f32 v64, v64, v65
	v_cvt_pk_bf16_f32 v65, v66, v67
	s_nop 0
	global_store_dwordx2 v4, v[64:65], s[26:27]
	v_mul_f32_e32 v68, v68, v208
	v_mul_f32_e32 v69, v69, v208
	v_mul_f32_e32 v70, v70, v208
	v_mul_f32_e32 v71, v71, v208
	v_fma_f32 v68, v68, v36, v52
	v_fma_f32 v69, v69, v37, v53
	v_fma_f32 v70, v70, v38, v54
	v_fma_f32 v71, v71, v39, v55
	v_cvt_pk_bf16_f32 v68, v68, v69
	v_cvt_pk_bf16_f32 v69, v70, v71
	s_nop 0
	global_store_dwordx2 v4, v[68:69], s[26:27] offset:512
	v_mul_f32_e32 v72, v72, v208
	v_mul_f32_e32 v73, v73, v208
	v_mul_f32_e32 v74, v74, v208
	v_mul_f32_e32 v75, v75, v208
	v_fma_f32 v72, v72, v40, v56
	v_fma_f32 v73, v73, v41, v57
	v_fma_f32 v74, v74, v42, v58
	v_fma_f32 v75, v75, v43, v59
	v_cvt_pk_bf16_f32 v72, v72, v73
	v_cvt_pk_bf16_f32 v73, v74, v75
	s_nop 0
	global_store_dwordx2 v4, v[72:73], s[26:27] offset:1024
	v_mul_f32_e32 v76, v76, v208
	v_mul_f32_e32 v77, v77, v208
	v_mul_f32_e32 v78, v78, v208
	v_mul_f32_e32 v79, v79, v208
	v_fma_f32 v76, v76, v44, v60
	v_fma_f32 v77, v77, v45, v61
	v_fma_f32 v78, v78, v46, v62
	v_fma_f32 v79, v79, v47, v63
	v_cvt_pk_bf16_f32 v76, v76, v77
	v_cvt_pk_bf16_f32 v77, v78, v79
	s_nop 0
	global_store_dwordx2 v4, v[76:77], s[26:27] offset:1536
	s_add_u32 s26, s26, 0x800
	s_addc_u32 s27, s27, 0
	s_waitcnt vmcnt(12)
; __device__ __forceinline__ int get_bid() { return 2 * get_rbid() + get_hb(); }
; template <bool PART, bool SRC16 = false>
; __device__ __forceinline__ void normmod_row2(const void* __restrict__ srcv, const float* __restrict__ g, const float* __restrict__ sh, const float* __restrict__ sc, bf16_t* __restrict__ dst, int lane, const float* __restrict__ bsh = nullptr) {
;     ...
;     else { v[0][i] = __builtin_nontemporal_load((const f32x4*)((const float*)srcv + lane * 4 + 256 * i)); v[1][i] = __builtin_nontemporal_load((const f32x4*)((const float*)srcv + 1024 + lane * 4 + 256 * i)); }
;   }
; #pragma unroll
;   for (int i = 0; i < 4; ++i) {
;     ss0 += v[0][i][0] * v[0][i][0] + v[0][i][1] * v[0][i][1] + v[0][i][2] * v[0][i][2] + v[0][i][3] * v[0][i][3];
;     ss1 += v[1][i][0] * v[1][i][0] + v[1][i][1] * v[1][i][1] + v[1][i][2] * v[1][i][2] + v[1][i][3] * v[1][i][3];
;   }
;   ss0 = wave_sum(ss0); ss1 = wave_sum(ss1);
;   const float r0 = rsqrtf(ss0 * (1.0f / 1024.0f) + 1e-6f), r1 = rsqrtf(ss1 * (1.0f / 1024.0f) + 1e-6f);
; #pragma unroll
;   for (int i = 0; i < 4; ++i) {
;     const int k = lane * 4 + 256 * i;
;     const f32x4 g4 = *(const f32x4*)(g + k);
;     f32x4 s4 = *(const f32x4*)(sh + k), c4 = *(const f32x4*)(sc + k);
;     if (PART) {
; #pragma unroll
;       for (int q = 1; q < 4; ++q) { s4 += *(const f32x4*)(sh + (size_t)q * 110592 + k); c4 += *(const f32x4*)(sc + (size_t)q * 110592 + k); }
;       s4 += *(const f32x4*)(bsh + k); c4 += *(const f32x4*)(bsh + 1024 + k);
;     }
;     float y[4], z[4];
; #pragma unroll
;     for (int j = 0; j < 4; ++j) { const float gm = g4[j] * (1.f + c4[j]); y[j] = (v[0][i][j] * r0) * gm + s4[j]; z[j] = (v[1][i][j] * r1) * gm + s4[j]; }
;     uint2 u; u.x = pack2(y[0], y[1]); u.y = pack2(y[2], y[3]);
;     *(uint2*)(dst + k) = u;
;     u.x = pack2(z[0], z[1]); u.y = pack2(z[2], z[3]);
;     *(uint2*)(dst + 1024 + k) = u;
; __device__ __forceinline__ void phase_normmod_kv(CP& p) {
;     ...
;   for (int r = (get_bid() * 4 + wv) * 2; r < 18432; r += VGRID * 8) {
;     const int b = r / 2304, pp = r - b * 2304;
;     const float* src; const float* mv;
;     if (pp < 256) { src = p.ctx + ((size_t)b * 256 + pp) * 1024; mv = p.modp + (size_t)8 * 6144; }
;     else { src = p.x + ((size_t)b * 2048 + pp - 256) * 1024; mv = p.modp + (size_t)b * 6144; }
;     normmod_row2<true>(src, g, mv, mv + 1024, p.hxc + (size_t)r * 1024, lane, p.mod_b);
	v_mul_f32_e32 v200, v81, v81
	v_mul_f32_e32 v201, v85, v85
	v_mul_f32_e32 v202, v89, v89
	v_mul_f32_e32 v203, v93, v93
	v_fma_f32 v200, v80, v80, v200
	v_fma_f32 v201, v84, v84, v201
	v_fma_f32 v202, v88, v88, v202
	v_fma_f32 v203, v92, v92, v203
	v_fma_f32 v200, v82, v82, v200
	v_fma_f32 v201, v86, v86, v201
	v_fma_f32 v202, v90, v90, v202
	v_fma_f32 v203, v94, v94, v203
	v_fma_f32 v200, v83, v83, v200
	v_fma_f32 v201, v87, v87, v201
	v_fma_f32 v202, v91, v91, v202
	v_fma_f32 v203, v95, v95, v203
	v_add_f32_e32 v204, v200, v201
	v_add_f32_e32 v204, v204, v202
	v_add_f32_e32 v204, v204, v203
	v_mov_b32_e32 v205, v204
	s_nop 1
	v_permlane32_swap_b32 v204, v205
	s_nop 1
	v_add_f32_e32 v204, v204, v205
	v_mov_b32_e32 v205, v204
	s_nop 1
	v_permlane16_swap_b32 v204, v205
	s_nop 1
	v_add_f32_e32 v204, v204, v205
	s_nop 1
	v_add_f32_dpp v204, v204, v204 row_ror:8 row_mask:0xf bank_mask:0xf
	s_nop 1
	v_add_f32_dpp v204, v204, v204 row_ror:4 row_mask:0xf bank_mask:0xf
	s_nop 1
	v_add_f32_dpp v204, v204, v204 row_ror:2 row_mask:0xf bank_mask:0xf
	s_nop 1
	v_add_f32_dpp v204, v204, v204 row_ror:1 row_mask:0xf bank_mask:0xf
	s_nop 1
	v_fma_f32 v206, v204, v211, v210
	v_mul_f32_e32 v207, 0x4b800000, v206
	v_cmp_gt_f32_e32 vcc, 0x800000, v206
	s_nop 1
	v_cndmask_b32_e32 v207, v206, v207, vcc
	v_rsq_f32_e32 v208, v207
	s_nop 1
	v_mul_f32_e32 v207, 0x45800000, v208
	v_cndmask_b32_e32 v208, v208, v207, vcc
	v_mul_f32_e32 v80, v80, v208
	v_mul_f32_e32 v81, v81, v208
	v_mul_f32_e32 v82, v82, v208
	v_mul_f32_e32 v83, v83, v208
	v_fma_f32 v80, v80, v32, v48
	v_fma_f32 v81, v81, v33, v49
	v_fma_f32 v82, v82, v34, v50
	v_fma_f32 v83, v83, v35, v51
	v_cvt_pk_bf16_f32 v80, v80, v81
	v_cvt_pk_bf16_f32 v81, v82, v83
	s_nop 0
	global_store_dwordx2 v4, v[80:81], s[26:27]
	v_mul_f32_e32 v84, v84, v208
	v_mul_f32_e32 v85, v85, v208
	v_mul_f32_e32 v86, v86, v208
	v_mul_f32_e32 v87, v87, v208
	v_fma_f32 v84, v84, v36, v52
	v_fma_f32 v85, v85, v37, v53
	v_fma_f32 v86, v86, v38, v54
	v_fma_f32 v87, v87, v39, v55
	v_cvt_pk_bf16_f32 v84, v84, v85
	v_cvt_pk_bf16_f32 v85, v86, v87
	s_nop 0
	global_store_dwordx2 v4, v[84:85], s[26:27] offset:512
	v_mul_f32_e32 v88, v88, v208
	v_mul_f32_e32 v89, v89, v208
	v_mul_f32_e32 v90, v90, v208
	v_mul_f32_e32 v91, v91, v208
	v_fma_f32 v88, v88, v40, v56
	v_fma_f32 v89, v89, v41, v57
	v_fma_f32 v90, v90, v42, v58
	v_fma_f32 v91, v91, v43, v59
	v_cvt_pk_bf16_f32 v88, v88, v89
	v_cvt_pk_bf16_f32 v89, v90, v91
	s_nop 0
	global_store_dwordx2 v4, v[88:89], s[26:27] offset:1024
	v_mul_f32_e32 v92, v92, v208
	v_mul_f32_e32 v93, v93, v208
	v_mul_f32_e32 v94, v94, v208
	v_mul_f32_e32 v95, v95, v208
	v_fma_f32 v92, v92, v44, v60
	v_fma_f32 v93, v93, v45, v61
	v_fma_f32 v94, v94, v46, v62
	v_fma_f32 v95, v95, v47, v63
	v_cvt_pk_bf16_f32 v92, v92, v93
	v_cvt_pk_bf16_f32 v93, v94, v95
	s_nop 0
	global_store_dwordx2 v4, v[92:93], s[26:27] offset:1536
	s_add_u32 s26, s26, 0x800
	s_addc_u32 s27, s27, 0
	s_add_u32 s28, s8, 0x2a000
	s_addc_u32 s29, s9, 0
	s_add_u32 s16, s28, 0x1000
	s_addc_u32 s17, s29, 0
	global_load_dwordx4 v[112:115], v3, s[4:5]
	global_load_dwordx4 v[116:119], v3, s[18:19]
	global_load_dwordx4 v[120:123], v3, s[10:11]
	global_load_dwordx4 v[124:127], v3, s[28:29]
	global_load_dwordx4 v[128:131], v13, s[28:29]
	global_load_dwordx4 v[132:135], v14, s[28:29]
	global_load_dwordx4 v[136:139], v15, s[28:29]
	global_load_dwordx4 v[140:143], v3, s[16:17]
	global_load_dwordx4 v[144:147], v13, s[16:17]
	global_load_dwordx4 v[148:151], v14, s[16:17]
	global_load_dwordx4 v[152:155], v15, s[16:17]
	global_load_dwordx4 v[156:159], v3, s[4:5] offset:1024
	global_load_dwordx4 v[160:163], v3, s[18:19] offset:1024
	global_load_dwordx4 v[164:167], v3, s[10:11] offset:1024
	global_load_dwordx4 v[168:171], v3, s[28:29] offset:1024
	global_load_dwordx4 v[172:175], v13, s[28:29] offset:1024
	global_load_dwordx4 v[176:179], v14, s[28:29] offset:1024
	global_load_dwordx4 v[180:183], v15, s[28:29] offset:1024
	global_load_dwordx4 v[184:187], v3, s[16:17] offset:1024
	global_load_dwordx4 v[188:191], v13, s[16:17] offset:1024
	global_load_dwordx4 v[192:195], v14, s[16:17] offset:1024
	global_load_dwordx4 v[196:199], v15, s[16:17] offset:1024
	s_waitcnt vmcnt(0)
	v_pk_add_f32 v[48:49], v[124:125], v[128:129]
	v_pk_add_f32 v[48:49], v[48:49], v[132:133]
	v_pk_add_f32 v[48:49], v[48:49], v[136:137]
	v_pk_add_f32 v[32:33], v[140:141], v[144:145]
	v_pk_add_f32 v[32:33], v[32:33], v[148:149]
	v_pk_add_f32 v[32:33], v[32:33], v[152:153]
	v_pk_add_f32 v[50:51], v[126:127], v[130:131]
	v_pk_add_f32 v[50:51], v[50:51], v[134:135]
	v_pk_add_f32 v[50:51], v[50:51], v[138:139]
	v_pk_add_f32 v[34:35], v[142:143], v[146:147]
	v_pk_add_f32 v[34:35], v[34:35], v[150:151]
	v_pk_add_f32 v[34:35], v[34:35], v[154:155]
	v_add_f32_e32 v48, v116, v48
	v_add_f32_e32 v32, v120, v32
	v_add_f32_e32 v32, 1.0, v32
	v_mul_f32_e32 v32, v112, v32
	v_add_f32_e32 v49, v117, v49
	v_add_f32_e32 v33, v121, v33
	v_add_f32_e32 v33, 1.0, v33
	v_mul_f32_e32 v33, v113, v33
	v_add_f32_e32 v50, v118, v50
	v_add_f32_e32 v34, v122, v34
	v_add_f32_e32 v34, 1.0, v34
	v_mul_f32_e32 v34, v114, v34
	v_add_f32_e32 v51, v119, v51
	v_add_f32_e32 v35, v123, v35
	v_add_f32_e32 v35, 1.0, v35
	v_mul_f32_e32 v35, v115, v35
	v_pk_add_f32 v[52:53], v[168:169], v[172:173]
	v_pk_add_f32 v[52:53], v[52:53], v[176:177]
	v_pk_add_f32 v[52:53], v[52:53], v[180:181]
	v_pk_add_f32 v[36:37], v[184:185], v[188:189]
	v_pk_add_f32 v[36:37], v[36:37], v[192:193]
	v_pk_add_f32 v[36:37], v[36:37], v[196:197]
	v_pk_add_f32 v[54:55], v[170:171], v[174:175]
	v_pk_add_f32 v[54:55], v[54:55], v[178:179]
	v_pk_add_f32 v[54:55], v[54:55], v[182:183]
; __device__ __forceinline__ int get_bid() { return 2 * get_rbid() + get_hb(); }
; template <bool PART, bool SRC16 = false>
; __device__ __forceinline__ void normmod_row2(const void* __restrict__ srcv, const float* __restrict__ g, const float* __restrict__ sh, const float* __restrict__ sc, bf16_t* __restrict__ dst, int lane, const float* __restrict__ bsh = nullptr) {
;     ...
;     else { v[0][i] = __builtin_nontemporal_load((const f32x4*)((const float*)srcv + lane * 4 + 256 * i)); v[1][i] = __builtin_nontemporal_load((const f32x4*)((const float*)srcv + 1024 + lane * 4 + 256 * i)); }
;   }
; #pragma unroll
;   for (int i = 0; i < 4; ++i) {
;     ss0 += v[0][i][0] * v[0][i][0] + v[0][i][1] * v[0][i][1] + v[0][i][2] * v[0][i][2] + v[0][i][3] * v[0][i][3];
;     ss1 += v[1][i][0] * v[1][i][0] + v[1][i][1] * v[1][i][1] + v[1][i][2] * v[1][i][2] + v[1][i][3] * v[1][i][3];
;   }
;   ss0 = wave_sum(ss0); ss1 = wave_sum(ss1);
;   const float r0 = rsqrtf(ss0 * (1.0f / 1024.0f) + 1e-6f), r1 = rsqrtf(ss1 * (1.0f / 1024.0f) + 1e-6f);
; #pragma unroll
;   for (int i = 0; i < 4; ++i) {
;     const int k = lane * 4 + 256 * i;
;     const f32x4 g4 = *(const f32x4*)(g + k);
;     f32x4 s4 = *(const f32x4*)(sh + k), c4 = *(const f32x4*)(sc + k);
;     if (PART) {
; #pragma unroll
;       for (int q = 1; q < 4; ++q) { s4 += *(const f32x4*)(sh + (size_t)q * 110592 + k); c4 += *(const f32x4*)(sc + (size_t)q * 110592 + k); }
;       s4 += *(const f32x4*)(bsh + k); c4 += *(const f32x4*)(bsh + 1024 + k);
;     }
;     float y[4], z[4];
; #pragma unroll
;     for (int j = 0; j < 4; ++j) { const float gm = g4[j] * (1.f + c4[j]); y[j] = (v[0][i][j] * r0) * gm + s4[j]; z[j] = (v[1][i][j] * r1) * gm + s4[j]; }
;     uint2 u; u.x = pack2(y[0], y[1]); u.y = pack2(y[2], y[3]);
;     *(uint2*)(dst + k) = u;
;     u.x = pack2(z[0], z[1]); u.y = pack2(z[2], z[3]);
;     *(uint2*)(dst + 1024 + k) = u;
; __device__ __forceinline__ void phase_normmod_kv(CP& p) {
;     ...
;   for (int r = (get_bid() * 4 + wv) * 2; r < 18432; r += VGRID * 8) {
;     const int b = r / 2304, pp = r - b * 2304;
;     const float* src; const float* mv;
;     if (pp < 256) { src = p.ctx + ((size_t)b * 256 + pp) * 1024; mv = p.modp + (size_t)8 * 6144; }
;     else { src = p.x + ((size_t)b * 2048 + pp - 256) * 1024; mv = p.modp + (size_t)b * 6144; }
;     normmod_row2<true>(src, g, mv, mv + 1024, p.hxc + (size_t)r * 1024, lane, p.mod_b);
	v_pk_add_f32 v[38:39], v[186:187], v[190:191]
	v_pk_add_f32 v[38:39], v[38:39], v[194:195]
	v_pk_add_f32 v[38:39], v[38:39], v[198:199]
	v_add_f32_e32 v52, v160, v52
	v_add_f32_e32 v36, v164, v36
	v_add_f32_e32 v36, 1.0, v36
	v_mul_f32_e32 v36, v156, v36
	v_add_f32_e32 v53, v161, v53
	v_add_f32_e32 v37, v165, v37
	v_add_f32_e32 v37, 1.0, v37
	v_mul_f32_e32 v37, v157, v37
	v_add_f32_e32 v54, v162, v54
	v_add_f32_e32 v38, v166, v38
	v_add_f32_e32 v38, 1.0, v38
	v_mul_f32_e32 v38, v158, v38
	v_add_f32_e32 v55, v163, v55
	v_add_f32_e32 v39, v167, v39
	v_add_f32_e32 v39, 1.0, v39
	v_mul_f32_e32 v39, v159, v39
	global_load_dwordx4 v[112:115], v3, s[4:5] offset:2048
	global_load_dwordx4 v[116:119], v3, s[18:19] offset:2048
	global_load_dwordx4 v[120:123], v3, s[10:11] offset:2048
	global_load_dwordx4 v[124:127], v3, s[28:29] offset:2048
	global_load_dwordx4 v[128:131], v13, s[28:29] offset:2048
	global_load_dwordx4 v[132:135], v14, s[28:29] offset:2048
	global_load_dwordx4 v[136:139], v15, s[28:29] offset:2048
	global_load_dwordx4 v[140:143], v3, s[16:17] offset:2048
	global_load_dwordx4 v[144:147], v13, s[16:17] offset:2048
	global_load_dwordx4 v[148:151], v14, s[16:17] offset:2048
	global_load_dwordx4 v[152:155], v15, s[16:17] offset:2048
	global_load_dwordx4 v[156:159], v3, s[4:5] offset:3072
	global_load_dwordx4 v[160:163], v3, s[18:19] offset:3072
	global_load_dwordx4 v[164:167], v3, s[10:11] offset:3072
	global_load_dwordx4 v[168:171], v3, s[28:29] offset:3072
	global_load_dwordx4 v[172:175], v13, s[28:29] offset:3072
	global_load_dwordx4 v[176:179], v14, s[28:29] offset:3072
	global_load_dwordx4 v[180:183], v15, s[28:29] offset:3072
	global_load_dwordx4 v[184:187], v3, s[16:17] offset:3072
	global_load_dwordx4 v[188:191], v13, s[16:17] offset:3072
	global_load_dwordx4 v[192:195], v14, s[16:17] offset:3072
	global_load_dwordx4 v[196:199], v15, s[16:17] offset:3072
	s_waitcnt vmcnt(0)
	v_pk_add_f32 v[56:57], v[124:125], v[128:129]
	v_pk_add_f32 v[56:57], v[56:57], v[132:133]
	v_pk_add_f32 v[56:57], v[56:57], v[136:137]
	v_pk_add_f32 v[40:41], v[140:141], v[144:145]
	v_pk_add_f32 v[40:41], v[40:41], v[148:149]
	v_pk_add_f32 v[40:41], v[40:41], v[152:153]
	v_pk_add_f32 v[58:59], v[126:127], v[130:131]
	v_pk_add_f32 v[58:59], v[58:59], v[134:135]
	v_pk_add_f32 v[58:59], v[58:59], v[138:139]
	v_pk_add_f32 v[42:43], v[142:143], v[146:147]
	v_pk_add_f32 v[42:43], v[42:43], v[150:151]
	v_pk_add_f32 v[42:43], v[42:43], v[154:155]
	v_add_f32_e32 v56, v116, v56
	v_add_f32_e32 v40, v120, v40
	v_add_f32_e32 v40, 1.0, v40
	v_mul_f32_e32 v40, v112, v40
	v_add_f32_e32 v57, v117, v57
	v_add_f32_e32 v41, v121, v41
	v_add_f32_e32 v41, 1.0, v41
	v_mul_f32_e32 v41, v113, v41
	v_add_f32_e32 v58, v118, v58
	v_add_f32_e32 v42, v122, v42
	v_add_f32_e32 v42, 1.0, v42
	v_mul_f32_e32 v42, v114, v42
	v_add_f32_e32 v59, v119, v59
	v_add_f32_e32 v43, v123, v43
	v_add_f32_e32 v43, 1.0, v43
	v_mul_f32_e32 v43, v115, v43
	v_pk_add_f32 v[60:61], v[168:169], v[172:173]
	v_pk_add_f32 v[60:61], v[60:61], v[176:177]
	v_pk_add_f32 v[60:61], v[60:61], v[180:181]
	v_pk_add_f32 v[44:45], v[184:185], v[188:189]
	v_pk_add_f32 v[44:45], v[44:45], v[192:193]
	v_pk_add_f32 v[44:45], v[44:45], v[196:197]
	v_pk_add_f32 v[62:63], v[170:171], v[174:175]
	v_pk_add_f32 v[62:63], v[62:63], v[178:179]
	v_pk_add_f32 v[62:63], v[62:63], v[182:183]
	v_pk_add_f32 v[46:47], v[186:187], v[190:191]
	v_pk_add_f32 v[46:47], v[46:47], v[194:195]
	v_pk_add_f32 v[46:47], v[46:47], v[198:199]
	v_add_f32_e32 v60, v160, v60
	v_add_f32_e32 v44, v164, v44
	v_add_f32_e32 v44, 1.0, v44
	v_mul_f32_e32 v44, v156, v44
	v_add_f32_e32 v61, v161, v61
	v_add_f32_e32 v45, v165, v45
	v_add_f32_e32 v45, 1.0, v45
	v_mul_f32_e32 v45, v157, v45
	v_add_f32_e32 v62, v162, v62
	v_add_f32_e32 v46, v166, v46
	v_add_f32_e32 v46, 1.0, v46
	v_mul_f32_e32 v46, v158, v46
	v_add_f32_e32 v63, v163, v63
	v_add_f32_e32 v47, v167, v47
	v_add_f32_e32 v47, 1.0, v47
	v_mul_f32_e32 v47, v159, v47
	v_mul_f32_e32 v200, v97, v97
	v_mul_f32_e32 v201, v101, v101
	v_mul_f32_e32 v202, v105, v105
	v_mul_f32_e32 v203, v109, v109
	v_fma_f32 v200, v96, v96, v200
	v_fma_f32 v201, v100, v100, v201
	v_fma_f32 v202, v104, v104, v202
	v_fma_f32 v203, v108, v108, v203
	v_fma_f32 v200, v98, v98, v200
	v_fma_f32 v201, v102, v102, v201
	v_fma_f32 v202, v106, v106, v202
	v_fma_f32 v203, v110, v110, v203
	v_fma_f32 v200, v99, v99, v200
	v_fma_f32 v201, v103, v103, v201
	v_fma_f32 v202, v107, v107, v202
	v_fma_f32 v203, v111, v111, v203
	v_add_f32_e32 v204, v200, v201
	v_add_f32_e32 v204, v204, v202
	v_add_f32_e32 v204, v204, v203
	v_mov_b32_e32 v205, v204
	s_nop 1
	v_permlane32_swap_b32 v204, v205
	s_nop 1
	v_add_f32_e32 v204, v204, v205
	v_mov_b32_e32 v205, v204
	s_nop 1
	v_permlane16_swap_b32 v204, v205
	s_nop 1
	v_add_f32_e32 v204, v204, v205
	s_nop 1
	v_add_f32_dpp v204, v204, v204 row_ror:8 row_mask:0xf bank_mask:0xf
	s_nop 1
	v_add_f32_dpp v204, v204, v204 row_ror:4 row_mask:0xf bank_mask:0xf
	s_nop 1
	v_add_f32_dpp v204, v204, v204 row_ror:2 row_mask:0xf bank_mask:0xf
	s_nop 1
	v_add_f32_dpp v204, v204, v204 row_ror:1 row_mask:0xf bank_mask:0xf
	s_nop 1
	v_fma_f32 v206, v204, v211, v210
	v_mul_f32_e32 v207, 0x4b800000, v206
	v_cmp_gt_f32_e32 vcc, 0x800000, v206
	s_nop 1
	v_cndmask_b32_e32 v207, v206, v207, vcc
	v_rsq_f32_e32 v208, v207
	s_nop 1
	v_mul_f32_e32 v207, 0x45800000, v208
	v_cndmask_b32_e32 v208, v208, v207, vcc
	v_mul_f32_e32 v96, v96, v208
	v_mul_f32_e32 v97, v97, v208
	v_mul_f32_e32 v98, v98, v208
	v_mul_f32_e32 v99, v99, v208
	v_fma_f32 v96, v96, v32, v48
	v_fma_f32 v97, v97, v33, v49
	v_fma_f32 v98, v98, v34, v50
	v_fma_f32 v99, v99, v35, v51
	v_cvt_pk_bf16_f32 v96, v96, v97
	v_cvt_pk_bf16_f32 v97, v98, v99
	s_nop 0
	global_store_dwordx2 v4, v[96:97], s[30:31]
	v_mul_f32_e32 v100, v100, v208
	v_mul_f32_e32 v101, v101, v208
	v_mul_f32_e32 v102, v102, v208
	v_mul_f32_e32 v103, v103, v208
	v_fma_f32 v100, v100, v36, v52
	v_fma_f32 v101, v101, v37, v53
	v_fma_f32 v102, v102, v38, v54
	v_fma_f32 v103, v103, v39, v55
	v_cvt_pk_bf16_f32 v100, v100, v101
	v_cvt_pk_bf16_f32 v101, v102, v103
	s_nop 0
	global_store_dwordx2 v4, v[100:101], s[30:31] offset:512
	v_mul_f32_e32 v104, v104, v208
	v_mul_f32_e32 v105, v105, v208
	v_mul_f32_e32 v106, v106, v208
	v_mul_f32_e32 v107, v107, v208
	v_fma_f32 v104, v104, v40, v56
	v_fma_f32 v105, v105, v41, v57
	v_fma_f32 v106, v106, v42, v58
	v_fma_f32 v107, v107, v43, v59
	v_cvt_pk_bf16_f32 v104, v104, v105
	v_cvt_pk_bf16_f32 v105, v106, v107
	s_nop 0
	global_store_dwordx2 v4, v[104:105], s[30:31] offset:1024
	v_mul_f32_e32 v108, v108, v208
	v_mul_f32_e32 v109, v109, v208
	v_mul_f32_e32 v110, v110, v208
	v_mul_f32_e32 v111, v111, v208
	v_fma_f32 v108, v108, v44, v60
	v_fma_f32 v109, v109, v45, v61
	v_fma_f32 v110, v110, v46, v62
	v_fma_f32 v111, v111, v47, v63
	v_cvt_pk_bf16_f32 v108, v108, v109
	v_cvt_pk_bf16_f32 v109, v110, v111
	s_nop 0
	global_store_dwordx2 v4, v[108:109], s[30:31] offset:1536

; __device__ __forceinline__ int get_tid() { int t = threadIdx.x & 255; asm volatile("" : "+v"(t)); return t; }
; __device__ __forceinline__ int get_bid() { return 2 * get_rbid() + get_hb(); }
; template <bool PART, bool SRC16 = false>
; __device__ __forceinline__ void normmod_row2(const void* __restrict__ srcv, const float* __restrict__ g, const float* __restrict__ sh, const float* __restrict__ sc, bf16_t* __restrict__ dst, int lane, const float* __restrict__ bsh = nullptr) {
;   f32x4 v[2][4]; float ss0 = 0.f, ss1 = 0.f;
; #pragma unroll
;   for (int i = 0; i < 4; ++i) {
;     if (SRC16) { v[0][i] = ld4_bf16((const bf16_t*)srcv + lane * 4 + 256 * i); v[1][i] = ld4_bf16((const bf16_t*)srcv + 1024 + lane * 4 + 256 * i); }
;     else { v[0][i] = __builtin_nontemporal_load((const f32x4*)((const float*)srcv + lane * 4 + 256 * i)); v[1][i] = __builtin_nontemporal_load((const f32x4*)((const float*)srcv + 1024 + lane * 4 + 256 * i)); }
;   }
; #pragma unroll
;   for (int i = 0; i < 4; ++i) {
;     ss0 += v[0][i][0] * v[0][i][0] + v[0][i][1] * v[0][i][1] + v[0][i][2] * v[0][i][2] + v[0][i][3] * v[0][i][3];
;     ss1 += v[1][i][0] * v[1][i][0] + v[1][i][1] * v[1][i][1] + v[1][i][2] * v[1][i][2] + v[1][i][3] * v[1][i][3];
;   }
;   ss0 = wave_sum(ss0); ss1 = wave_sum(ss1);
; __device__ __forceinline__ void phase_normmod_x(CP& p, const float* g, int layer, int chunk) {
;   const int lane = get_tid() & 63, wv = get_tid() >> 6;
;   for (int r = (get_bid() * 4 + wv) * 2; r < 16384; r += VGRID * 8) {
;     const int b = r >> 11;
;     const float* mv = p.modv + (size_t)(layer * 9 + b) * 6144 + chunk * 1024;
;     normmod_row2<false, true>(p.X16 + (size_t)r * 1024, g, mv, mv + 1024, p.hxc + (size_t)r * 1024, lane);
.LBB0_2252:
	v_lshl_add_u64 v[28:29], v[12:13], 0, v[8:9]
	global_load_dwordx4 v[36:39], v[10:11], off offset:1024
	global_load_dwordx4 v[40:43], v[10:11], off offset:2048
	global_load_dwordx4 v[44:47], v[10:11], off offset:3072
	global_load_dwordx2 v[80:81], v[28:29], off offset:512
	global_load_dwordx2 v[82:83], v[28:29], off
	global_load_dwordx2 v[84:85], v[28:29], off offset:2560
	global_load_dwordx2 v[86:87], v[28:29], off offset:2048
	global_load_dwordx2 v[88:89], v[28:29], off offset:1536
	global_load_dwordx2 v[90:91], v[28:29], off offset:1024
	global_load_dwordx2 v[92:93], v[28:29], off offset:3584
	global_load_dwordx2 v[94:95], v[28:29], off offset:3072
	v_ashrrev_i32_e32 v7, 11, v6
	v_mul_hi_i32_i24_e32 v29, 0x6000, v7
	v_mul_i32_i24_e32 v28, 0x6000, v7
	v_lshl_add_u64 v[28:29], s[8:9], 0, v[28:29]
	v_lshl_add_u64 v[64:65], v[28:29], 0, s[16:17]
	v_lshl_add_u64 v[28:29], v[28:29], 0, v[18:19]
	v_lshl_add_u64 v[96:97], v[64:65], 0, v[18:19]
	global_load_dwordx4 v[48:51], v[28:29], off
	global_load_dwordx4 v[52:55], v[28:29], off offset:1024
	v_lshl_add_u64 v[98:99], v[64:65], 0, v[20:21]
	v_lshl_add_u64 v[100:101], v[64:65], 0, v[22:23]
	global_load_dwordx4 v[56:59], v[28:29], off offset:2048
	global_load_dwordx4 v[60:63], v[28:29], off offset:3072
	v_lshl_add_u64 v[28:29], v[64:65], 0, v[24:25]
	global_load_dwordx4 v[64:67], v[96:97], off
	global_load_dwordx4 v[68:71], v[98:99], off
	global_load_dwordx4 v[72:75], v[100:101], off
	global_load_dwordx4 v[76:79], v[28:29], off
	v_add_u32_e32 v6, s10, v6
	v_cmp_lt_i32_e32 vcc, s11, v6
	s_or_b64 s[14:15], vcc, s[14:15]
	v_lshl_add_u64 v[26:27], v[14:15], 0, v[8:9]
	v_lshl_add_u64 v[12:13], v[12:13], 0, s[12:13]
	v_lshl_add_u64 v[14:15], v[14:15], 0, s[12:13]
	s_waitcnt vmcnt(15)
	v_and_b32_e32 v97, 0xffff0000, v80
	s_waitcnt vmcnt(14)
	v_and_b32_e32 v96, 0xffff0000, v82
	s_waitcnt vmcnt(13)
	v_and_b32_e32 v101, 0xffff0000, v84
	s_waitcnt vmcnt(12)
	v_and_b32_e32 v100, 0xffff0000, v86
	v_lshlrev_b32_e32 v29, 16, v80
	v_lshlrev_b32_e32 v28, 16, v82
	v_lshlrev_b32_e32 v98, 16, v83
	v_and_b32_e32 v80, 0xffff0000, v83
	v_lshlrev_b32_e32 v83, 16, v84
	v_lshlrev_b32_e32 v82, 16, v86
	v_lshlrev_b32_e32 v102, 16, v87
	v_and_b32_e32 v84, 0xffff0000, v87
	s_waitcnt vmcnt(11)
	v_lshlrev_b32_e32 v87, 16, v88
	s_waitcnt vmcnt(10)
	v_lshlrev_b32_e32 v86, 16, v90
	v_and_b32_e32 v105, 0xffff0000, v88
	v_and_b32_e32 v104, 0xffff0000, v90
	v_lshlrev_b32_e32 v106, 16, v91
	v_and_b32_e32 v88, 0xffff0000, v91
	s_waitcnt vmcnt(9)
	v_lshlrev_b32_e32 v91, 16, v92
	s_waitcnt vmcnt(8)
	v_lshlrev_b32_e32 v90, 16, v94
	v_and_b32_e32 v109, 0xffff0000, v92
	v_and_b32_e32 v108, 0xffff0000, v94
	v_lshlrev_b32_e32 v110, 16, v95
	v_and_b32_e32 v92, 0xffff0000, v95
	v_pk_mul_f32 v[94:95], v[96:97], v[96:97]
	v_pk_mul_f32 v[112:113], v[100:101], v[100:101]
	v_lshlrev_b32_e32 v99, 16, v81
	v_lshlrev_b32_e32 v103, 16, v85
	v_pk_mul_f32 v[114:115], v[104:105], v[104:105]
	v_pk_mul_f32 v[116:117], v[108:109], v[108:109]
	v_pk_fma_f32 v[94:95], v[28:29], v[28:29], v[94:95]
	v_pk_fma_f32 v[112:113], v[82:83], v[82:83], v[112:113]
	v_and_b32_e32 v81, 0xffff0000, v81
	v_and_b32_e32 v85, 0xffff0000, v85
	v_lshlrev_b32_e32 v107, 16, v89
	v_lshlrev_b32_e32 v111, 16, v93
	v_pk_fma_f32 v[114:115], v[86:87], v[86:87], v[114:115]
	v_pk_fma_f32 v[116:117], v[90:91], v[90:91], v[116:117]
	v_pk_fma_f32 v[94:95], v[98:99], v[98:99], v[94:95]
	v_pk_fma_f32 v[112:113], v[102:103], v[102:103], v[112:113]
	v_and_b32_e32 v89, 0xffff0000, v89
	v_and_b32_e32 v93, 0xffff0000, v93
	v_pk_fma_f32 v[114:115], v[106:107], v[106:107], v[114:115]
	v_pk_fma_f32 v[116:117], v[110:111], v[110:111], v[116:117]
	v_pk_fma_f32 v[94:95], v[80:81], v[80:81], v[94:95]
	v_pk_fma_f32 v[112:113], v[84:85], v[84:85], v[112:113]
	v_pk_fma_f32 v[114:115], v[88:89], v[88:89], v[114:115]
	v_pk_fma_f32 v[116:117], v[92:93], v[92:93], v[116:117]
	s_waitcnt vmcnt(3)
	v_add_f32_e32 v7, 1.0, v64
	v_add_f32_e32 v35, 1.0, v65
	s_waitcnt vmcnt(2)
	v_add_f32_e32 v68, 1.0, v68
	v_add_f32_e32 v69, 1.0, v69
	v_mov_b32_e32 v64, v112
	v_mov_b32_e32 v65, v94
	v_mov_b32_e32 v94, v113
	v_add_f32_e32 v118, 1.0, v66
	v_add_f32_e32 v119, 1.0, v67
	v_mov_b32_e32 v66, v116
	v_mov_b32_e32 v67, v114
	v_mul_f32_e32 v68, v36, v68
	v_mul_f32_e32 v69, v37, v69
	v_pk_add_f32 v[36:37], v[64:65], v[94:95]
	v_mov_b32_e32 v114, v117
	v_pk_add_f32 v[36:37], v[36:37], v[66:67]
	v_add_f32_e32 v70, 1.0, v70
	v_add_f32_e32 v71, 1.0, v71
	v_pk_add_f32 v[36:37], v[36:37], v[114:115]
	v_mul_f32_e32 v70, v38, v70
	v_mul_f32_e32 v71, v39, v71
	v_mov_b32_e32 v38, v36
	v_mov_b32_e32 v39, v37
	s_nop 1
	v_permlane32_swap_b32 v36, v38
	v_permlane32_swap_b32 v37, v39
	s_nop 1
	v_mul_f32_e32 v7, v2, v7
	s_waitcnt vmcnt(1)
	v_add_f32_e32 v72, 1.0, v72
	v_add_f32_e32 v73, 1.0, v73
	v_add_f32_e32 v74, 1.0, v74
	s_waitcnt lgkmcnt(0)
; __device__ __forceinline__ unsigned pack2(float a, float b) { unsigned r; asm("v_cvt_pk_bf16_f32 %0, %1, %2" : "=v"(r) : "v"(a), "v"(b)); return r; }
; template <bool PART, bool SRC16 = false>
; __device__ __forceinline__ void normmod_row2(const void* __restrict__ srcv, const float* __restrict__ g, const float* __restrict__ sh, const float* __restrict__ sc, bf16_t* __restrict__ dst, int lane, const float* __restrict__ bsh = nullptr) {
;     ...
;   ss0 = wave_sum(ss0); ss1 = wave_sum(ss1);
;   const float r0 = rsqrtf(ss0 * (1.0f / 1024.0f) + 1e-6f), r1 = rsqrtf(ss1 * (1.0f / 1024.0f) + 1e-6f);
; #pragma unroll
;   for (int i = 0; i < 4; ++i) {
;     const int k = lane * 4 + 256 * i;
;     const f32x4 g4 = *(const f32x4*)(g + k);
;     f32x4 s4 = *(const f32x4*)(sh + k), c4 = *(const f32x4*)(sc + k);
;     if (PART) {
; #pragma unroll
;       for (int q = 1; q < 4; ++q) { s4 += *(const f32x4*)(sh + (size_t)q * 110592 + k); c4 += *(const f32x4*)(sc + (size_t)q * 110592 + k); }
;       s4 += *(const f32x4*)(bsh + k); c4 += *(const f32x4*)(bsh + 1024 + k);
;     }
;     float y[4], z[4];
; #pragma unroll
;     for (int j = 0; j < 4; ++j) { const float gm = g4[j] * (1.f + c4[j]); y[j] = (v[0][i][j] * r0) * gm + s4[j]; z[j] = (v[1][i][j] * r1) * gm + s4[j]; }
;     uint2 u; u.x = pack2(y[0], y[1]); u.y = pack2(y[2], y[3]);
;     *(uint2*)(dst + k) = u;
;     u.x = pack2(z[0], z[1]); u.y = pack2(z[2], z[3]);
;     *(uint2*)(dst + 1024 + k) = u;
	v_pk_add_f32 v[36:37], v[36:37], v[38:39]
	v_mov_b32_e32 v38, v36
	v_mov_b32_e32 v39, v37
	s_nop 1
	v_permlane16_swap_b32 v36, v38
	v_permlane16_swap_b32 v37, v39
	s_nop 1
	v_add_f32_e32 v75, 1.0, v75
	s_waitcnt vmcnt(0)
	v_add_f32_e32 v76, 1.0, v76
	v_add_f32_e32 v77, 1.0, v77
	v_add_f32_e32 v78, 1.0, v78
	s_waitcnt lgkmcnt(0)
	v_pk_add_f32 v[36:37], v[36:37], v[38:39]
	s_nop 1
	v_add_f32_e32 v79, 1.0, v79
	v_mul_f32_e32 v35, v3, v35
	v_mul_f32_e32 v112, v4, v118
	v_mul_f32_e32 v113, v5, v119
	s_waitcnt lgkmcnt(0)
	v_add_f32_dpp v36, v36, v36 row_ror:8 row_mask:0xf bank_mask:0xf
	v_add_f32_dpp v37, v37, v37 row_ror:8 row_mask:0xf bank_mask:0xf
	s_nop 1
	s_nop 1
	v_mul_f32_e32 v40, v40, v72
	v_mul_f32_e32 v41, v41, v73
	v_mul_f32_e32 v42, v42, v74
	v_mul_f32_e32 v43, v43, v75
	s_waitcnt lgkmcnt(0)
	v_add_f32_dpp v36, v36, v36 row_ror:4 row_mask:0xf bank_mask:0xf
	v_add_f32_dpp v37, v37, v37 row_ror:4 row_mask:0xf bank_mask:0xf
	s_nop 1
	s_nop 1
	v_mul_f32_e32 v44, v44, v76
	v_mul_f32_e32 v45, v45, v77
	v_mul_f32_e32 v46, v46, v78
	v_mul_f32_e32 v47, v47, v79
	s_waitcnt lgkmcnt(0)
	v_add_f32_dpp v36, v36, v36 row_ror:2 row_mask:0xf bank_mask:0xf
	v_add_f32_dpp v37, v37, v37 row_ror:2 row_mask:0xf bank_mask:0xf
	s_nop 1
	s_nop 1
	s_waitcnt lgkmcnt(0)
	v_add_f32_dpp v36, v36, v36 row_ror:1 row_mask:0xf bank_mask:0xf
	v_add_f32_dpp v37, v37, v37 row_ror:1 row_mask:0xf bank_mask:0xf
	s_nop 1
	s_nop 0
	v_pk_fma_f32 v[36:37], v[36:37], s[18:19], v[16:17] op_sel_hi:[1,0,0]
	s_nop 0
	v_mul_f32_e32 v38, 0x4b800000, v37
	v_cmp_gt_f32_e64 s[4:5], s3, v37
	v_mul_f32_e32 v39, 0x4b800000, v36
	v_cmp_gt_f32_e32 vcc, s3, v36
	v_cndmask_b32_e64 v37, v37, v38, s[4:5]
	v_rsq_f32_e32 v37, v37
	v_cndmask_b32_e32 v36, v36, v39, vcc
	v_rsq_f32_e32 v36, v36
	v_mul_f32_e32 v38, 0x45800000, v37
	v_cndmask_b32_e64 v37, v37, v38, s[4:5]
	v_mul_f32_e32 v39, 0x45800000, v36
	v_cndmask_b32_e32 v36, v36, v39, vcc
	v_mul_f32_e32 v28, v37, v28
	v_mul_f32_e32 v38, v36, v82
	v_mul_f32_e32 v39, v37, v96
	v_mul_f32_e32 v64, v36, v100
	v_mul_f32_e32 v65, v37, v98
	v_mul_f32_e32 v66, v36, v102
	v_mul_f32_e32 v67, v37, v80
	v_mul_f32_e32 v29, v37, v29
	v_fma_f32 v28, v7, v28, v48
	v_mul_f32_e32 v72, v36, v84
	v_mul_f32_e32 v73, v36, v83
	v_mul_f32_e32 v74, v37, v97
	v_mul_f32_e32 v75, v36, v101
	v_mul_f32_e32 v76, v37, v99
	v_mul_f32_e32 v77, v36, v103
	v_mul_f32_e32 v78, v37, v81
	v_mul_f32_e32 v79, v36, v85
	v_mul_f32_e32 v80, v37, v86
	v_mul_f32_e32 v81, v36, v90
	v_mul_f32_e32 v82, v37, v104
	v_mul_f32_e32 v83, v36, v108
	v_mul_f32_e32 v84, v37, v106
	v_mul_f32_e32 v85, v36, v110
	v_mul_f32_e32 v86, v37, v88
	v_mul_f32_e32 v88, v36, v92
	v_mul_f32_e32 v87, v37, v87
	v_mul_f32_e32 v90, v36, v91
	v_mul_f32_e32 v91, v37, v105
	v_mul_f32_e32 v92, v36, v109
	v_mul_f32_e32 v94, v37, v107
	v_mul_f32_e32 v95, v36, v111
	v_mul_f32_e32 v37, v37, v89
	v_mul_f32_e32 v36, v36, v93
	v_fma_f32 v7, v7, v38, v48
	v_fma_f32 v38, v35, v39, v49
	v_fma_f32 v35, v35, v64, v49
	v_fma_f32 v39, v112, v65, v50
	v_fma_f32 v48, v112, v66, v50
	v_fma_f32 v49, v113, v67, v51
	v_fma_f32 v50, v29, v68, v52
	v_cvt_pk_bf16_f32 v28, v28, v38
	v_cvt_pk_bf16_f32 v29, v39, v49
	v_fmac_f32_e32 v51, v113, v72
	v_fma_f32 v52, v73, v68, v52
	v_fma_f32 v64, v74, v69, v53
	v_fma_f32 v53, v75, v69, v53
	v_fma_f32 v65, v76, v70, v54
	v_fma_f32 v54, v77, v70, v54
	v_fma_f32 v66, v78, v71, v55
	v_fmac_f32_e32 v55, v79, v71
	v_fma_f32 v67, v80, v40, v56
	v_fma_f32 v56, v81, v40, v56
	v_fma_f32 v68, v82, v41, v57
	v_fma_f32 v57, v83, v41, v57
	v_fma_f32 v69, v84, v42, v58
	v_fma_f32 v58, v85, v42, v58
	v_fma_f32 v70, v86, v43, v59
	v_fmac_f32_e32 v59, v88, v43
	v_fma_f32 v71, v87, v44, v60
	v_fma_f32 v60, v90, v44, v60
	v_fma_f32 v72, v91, v45, v61
	v_fma_f32 v61, v92, v45, v61
	v_fma_f32 v73, v94, v46, v62
	v_fma_f32 v62, v95, v46, v62
	v_fma_f32 v74, v37, v47, v63
	v_fmac_f32_e32 v63, v36, v47
	v_cvt_pk_bf16_f32 v36, v7, v35
	v_cvt_pk_bf16_f32 v37, v48, v51
	v_cvt_pk_bf16_f32 v38, v50, v64
	v_cvt_pk_bf16_f32 v39, v65, v66
	v_cvt_pk_bf16_f32 v40, v52, v53
	v_cvt_pk_bf16_f32 v41, v54, v55
	v_cvt_pk_bf16_f32 v42, v67, v68
	v_cvt_pk_bf16_f32 v43, v69, v70
	v_cvt_pk_bf16_f32 v44, v56, v57
	v_cvt_pk_bf16_f32 v45, v58, v59
	v_cvt_pk_bf16_f32 v46, v71, v72
	v_cvt_pk_bf16_f32 v47, v73, v74
	v_cvt_pk_bf16_f32 v48, v60, v61
	v_cvt_pk_bf16_f32 v49, v62, v63
	global_store_dwordx2 v[26:27], v[28:29], off
	global_store_dwordx2 v[26:27], v[36:37], off offset:2048
	global_store_dwordx2 v[26:27], v[38:39], off offset:512
	global_store_dwordx2 v[26:27], v[40:41], off offset:2560
	global_store_dwordx2 v[26:27], v[42:43], off offset:1024
	global_store_dwordx2 v[26:27], v[44:45], off offset:3072
	global_store_dwordx2 v[26:27], v[46:47], off offset:1536
	global_store_dwordx2 v[26:27], v[48:49], off offset:3584
	s_andn2_b64 exec, exec, s[14:15]
	s_cbranch_execnz .LBB0_2252

; __device__ __forceinline__ int get_tid() { int t = threadIdx.x & 255; asm volatile("" : "+v"(t)); return t; }
; __device__ __forceinline__ int get_bid() { return 2 * get_rbid() + get_hb(); }
; template <bool PART, bool SRC16 = false>
; __device__ __forceinline__ void normmod_row2(const void* __restrict__ srcv, const float* __restrict__ g, const float* __restrict__ sh, const float* __restrict__ sc, bf16_t* __restrict__ dst, int lane, const float* __restrict__ bsh = nullptr) {
;   f32x4 v[2][4]; float ss0 = 0.f, ss1 = 0.f;
; #pragma unroll
;   for (int i = 0; i < 4; ++i) {
;     if (SRC16) { v[0][i] = ld4_bf16((const bf16_t*)srcv + lane * 4 + 256 * i); v[1][i] = ld4_bf16((const bf16_t*)srcv + 1024 + lane * 4 + 256 * i); }
;     else { v[0][i] = __builtin_nontemporal_load((const f32x4*)((const float*)srcv + lane * 4 + 256 * i)); v[1][i] = __builtin_nontemporal_load((const f32x4*)((const float*)srcv + 1024 + lane * 4 + 256 * i)); }
;   }
; #pragma unroll
;   for (int i = 0; i < 4; ++i) {
;     ss0 += v[0][i][0] * v[0][i][0] + v[0][i][1] * v[0][i][1] + v[0][i][2] * v[0][i][2] + v[0][i][3] * v[0][i][3];
;     ss1 += v[1][i][0] * v[1][i][0] + v[1][i][1] * v[1][i][1] + v[1][i][2] * v[1][i][2] + v[1][i][3] * v[1][i][3];
;   }
;   ss0 = wave_sum(ss0); ss1 = wave_sum(ss1);
; __device__ __forceinline__ void phase_normmod_x(CP& p, const float* g, int layer, int chunk) {
;   const int lane = get_tid() & 63, wv = get_tid() >> 6;
;   for (int r = (get_bid() * 4 + wv) * 2; r < 16384; r += VGRID * 8) {
;     const int b = r >> 11;
;     const float* mv = p.modv + (size_t)(layer * 9 + b) * 6144 + chunk * 1024;
;     normmod_row2<false, true>(p.X16 + (size_t)r * 1024, g, mv, mv + 1024, p.hxc + (size_t)r * 1024, lane);
.LBB0_2565:
	v_lshl_add_u64 v[32:33], v[16:17], 0, v[8:9]
	global_load_dwordx4 v[40:43], v[10:11], off
	global_load_dwordx4 v[44:47], v[12:13], off
	global_load_dwordx4 v[48:51], v[14:15], off
	global_load_dwordx2 v[84:85], v[32:33], off offset:512
	global_load_dwordx2 v[86:87], v[32:33], off
	global_load_dwordx2 v[88:89], v[32:33], off offset:2560
	global_load_dwordx2 v[90:91], v[32:33], off offset:2048
	global_load_dwordx2 v[92:93], v[32:33], off offset:1536
	global_load_dwordx2 v[94:95], v[32:33], off offset:1024
	global_load_dwordx2 v[96:97], v[32:33], off offset:3584
	global_load_dwordx2 v[98:99], v[32:33], off offset:3072
	v_ashrrev_i32_e32 v7, 11, v6
	v_add_u32_e32 v7, 9, v7
	v_mul_hi_i32_i24_e32 v33, 0x6000, v7
	v_mul_i32_i24_e32 v32, 0x6000, v7
	v_lshl_add_u64 v[32:33], s[8:9], 0, v[32:33]
	v_lshl_add_u64 v[68:69], v[32:33], 0, s[10:11]
	v_lshl_add_u64 v[32:33], v[32:33], 0, v[22:23]
	v_lshl_add_u64 v[100:101], v[68:69], 0, v[22:23]
	global_load_dwordx4 v[52:55], v[32:33], off
	global_load_dwordx4 v[56:59], v[32:33], off offset:1024
	v_lshl_add_u64 v[102:103], v[68:69], 0, v[24:25]
	v_lshl_add_u64 v[104:105], v[68:69], 0, v[26:27]
	global_load_dwordx4 v[60:63], v[32:33], off offset:2048
	global_load_dwordx4 v[64:67], v[32:33], off offset:3072
	v_lshl_add_u64 v[32:33], v[68:69], 0, v[28:29]
	global_load_dwordx4 v[68:71], v[100:101], off
	global_load_dwordx4 v[72:75], v[102:103], off
	global_load_dwordx4 v[76:79], v[104:105], off
	global_load_dwordx4 v[80:83], v[32:33], off
	v_add_u32_e32 v6, s12, v6
	v_cmp_lt_i32_e32 vcc, s13, v6
	s_or_b64 s[16:17], vcc, s[16:17]
	v_lshl_add_u64 v[30:31], v[18:19], 0, v[8:9]
	v_lshl_add_u64 v[16:17], v[16:17], 0, s[14:15]
	v_lshl_add_u64 v[18:19], v[18:19], 0, s[14:15]
	s_waitcnt vmcnt(15)
	v_and_b32_e32 v101, 0xffff0000, v84
	s_waitcnt vmcnt(14)
	v_and_b32_e32 v100, 0xffff0000, v86
	s_waitcnt vmcnt(13)
	v_and_b32_e32 v105, 0xffff0000, v88
	s_waitcnt vmcnt(12)
	v_and_b32_e32 v104, 0xffff0000, v90
	v_lshlrev_b32_e32 v33, 16, v84
	v_lshlrev_b32_e32 v32, 16, v86
	v_lshlrev_b32_e32 v102, 16, v87
	v_and_b32_e32 v84, 0xffff0000, v87
	v_lshlrev_b32_e32 v87, 16, v88
	v_lshlrev_b32_e32 v86, 16, v90
	v_lshlrev_b32_e32 v106, 16, v91
	v_and_b32_e32 v88, 0xffff0000, v91
	s_waitcnt vmcnt(11)
	v_lshlrev_b32_e32 v91, 16, v92
	s_waitcnt vmcnt(10)
	v_lshlrev_b32_e32 v90, 16, v94
	v_and_b32_e32 v109, 0xffff0000, v92
	v_and_b32_e32 v108, 0xffff0000, v94
	v_lshlrev_b32_e32 v110, 16, v95
	v_and_b32_e32 v92, 0xffff0000, v95
	s_waitcnt vmcnt(9)
	v_lshlrev_b32_e32 v95, 16, v96
	s_waitcnt vmcnt(8)
	v_lshlrev_b32_e32 v94, 16, v98
	v_and_b32_e32 v113, 0xffff0000, v96
	v_and_b32_e32 v112, 0xffff0000, v98
	v_lshlrev_b32_e32 v114, 16, v99
	v_and_b32_e32 v96, 0xffff0000, v99
	v_pk_mul_f32 v[98:99], v[100:101], v[100:101]
	v_pk_mul_f32 v[116:117], v[104:105], v[104:105]
	v_lshlrev_b32_e32 v103, 16, v85
	v_lshlrev_b32_e32 v107, 16, v89
	v_pk_mul_f32 v[118:119], v[108:109], v[108:109]
	v_pk_mul_f32 v[120:121], v[112:113], v[112:113]
	v_pk_fma_f32 v[98:99], v[32:33], v[32:33], v[98:99]
	v_pk_fma_f32 v[116:117], v[86:87], v[86:87], v[116:117]
	v_and_b32_e32 v85, 0xffff0000, v85
	v_and_b32_e32 v89, 0xffff0000, v89
	v_lshlrev_b32_e32 v111, 16, v93
	v_lshlrev_b32_e32 v115, 16, v97
	v_pk_fma_f32 v[118:119], v[90:91], v[90:91], v[118:119]
	v_pk_fma_f32 v[120:121], v[94:95], v[94:95], v[120:121]
	v_pk_fma_f32 v[98:99], v[102:103], v[102:103], v[98:99]
	v_pk_fma_f32 v[116:117], v[106:107], v[106:107], v[116:117]
	v_and_b32_e32 v93, 0xffff0000, v93
	v_and_b32_e32 v97, 0xffff0000, v97
	v_pk_fma_f32 v[118:119], v[110:111], v[110:111], v[118:119]
	v_pk_fma_f32 v[120:121], v[114:115], v[114:115], v[120:121]
	v_pk_fma_f32 v[98:99], v[84:85], v[84:85], v[98:99]
	v_pk_fma_f32 v[116:117], v[88:89], v[88:89], v[116:117]
	v_pk_fma_f32 v[118:119], v[92:93], v[92:93], v[118:119]
	v_pk_fma_f32 v[120:121], v[96:97], v[96:97], v[120:121]
	v_mov_b32_e32 v122, v116
	v_mov_b32_e32 v123, v98
	v_mov_b32_e32 v98, v117
	v_mov_b32_e32 v116, v120
	v_mov_b32_e32 v117, v118
	s_waitcnt vmcnt(3)
	v_add_f32_e32 v7, 1.0, v68
	v_add_f32_e32 v39, 1.0, v69
	s_waitcnt vmcnt(2)
	v_add_f32_e32 v72, 1.0, v72
	v_add_f32_e32 v73, 1.0, v73
	v_pk_add_f32 v[68:69], v[122:123], v[98:99]
	v_mov_b32_e32 v118, v121
	v_mul_f32_e32 v72, v40, v72
	v_mul_f32_e32 v73, v41, v73
	v_pk_add_f32 v[40:41], v[68:69], v[116:117]
	v_add_f32_e32 v74, 1.0, v74
	v_add_f32_e32 v75, 1.0, v75
	v_pk_add_f32 v[40:41], v[40:41], v[118:119]
	v_mul_f32_e32 v74, v42, v74
	v_mul_f32_e32 v75, v43, v75
	v_mov_b32_e32 v42, v40
	v_mov_b32_e32 v43, v41
	s_nop 1
	v_permlane32_swap_b32 v40, v42
	v_permlane32_swap_b32 v41, v43
	s_nop 1
	v_add_f32_e32 v70, 1.0, v70
	v_add_f32_e32 v71, 1.0, v71
	s_waitcnt vmcnt(1)
	v_add_f32_e32 v76, 1.0, v76
	v_add_f32_e32 v77, 1.0, v77
	s_waitcnt lgkmcnt(0)
; __device__ __forceinline__ unsigned pack2(float a, float b) { unsigned r; asm("v_cvt_pk_bf16_f32 %0, %1, %2" : "=v"(r) : "v"(a), "v"(b)); return r; }
; template <bool PART, bool SRC16 = false>
; __device__ __forceinline__ void normmod_row2(const void* __restrict__ srcv, const float* __restrict__ g, const float* __restrict__ sh, const float* __restrict__ sc, bf16_t* __restrict__ dst, int lane, const float* __restrict__ bsh = nullptr) {
;     ...
;   ss0 = wave_sum(ss0); ss1 = wave_sum(ss1);
;   const float r0 = rsqrtf(ss0 * (1.0f / 1024.0f) + 1e-6f), r1 = rsqrtf(ss1 * (1.0f / 1024.0f) + 1e-6f);
; #pragma unroll
;   for (int i = 0; i < 4; ++i) {
;     const int k = lane * 4 + 256 * i;
;     const f32x4 g4 = *(const f32x4*)(g + k);
;     f32x4 s4 = *(const f32x4*)(sh + k), c4 = *(const f32x4*)(sc + k);
;     if (PART) {
; #pragma unroll
;       for (int q = 1; q < 4; ++q) { s4 += *(const f32x4*)(sh + (size_t)q * 110592 + k); c4 += *(const f32x4*)(sc + (size_t)q * 110592 + k); }
;       s4 += *(const f32x4*)(bsh + k); c4 += *(const f32x4*)(bsh + 1024 + k);
;     }
;     float y[4], z[4];
; #pragma unroll
;     for (int j = 0; j < 4; ++j) { const float gm = g4[j] * (1.f + c4[j]); y[j] = (v[0][i][j] * r0) * gm + s4[j]; z[j] = (v[1][i][j] * r1) * gm + s4[j]; }
;     uint2 u; u.x = pack2(y[0], y[1]); u.y = pack2(y[2], y[3]);
;     *(uint2*)(dst + k) = u;
;     u.x = pack2(z[0], z[1]); u.y = pack2(z[2], z[3]);
;     *(uint2*)(dst + 1024 + k) = u;
	v_pk_add_f32 v[40:41], v[40:41], v[42:43]
	v_mov_b32_e32 v42, v40
	v_mov_b32_e32 v43, v41
	s_nop 1
	v_permlane16_swap_b32 v40, v42
	v_permlane16_swap_b32 v41, v43
	s_nop 1
	v_mul_f32_e32 v7, v2, v7
	v_add_f32_e32 v78, 1.0, v78
	v_add_f32_e32 v79, 1.0, v79
	s_waitcnt vmcnt(0)
	v_add_f32_e32 v80, 1.0, v80
	s_waitcnt lgkmcnt(0)
	v_pk_add_f32 v[40:41], v[40:41], v[42:43]
	s_nop 1
	v_add_f32_e32 v81, 1.0, v81
	v_add_f32_e32 v82, 1.0, v82
	v_add_f32_e32 v83, 1.0, v83
	v_mul_f32_e32 v39, v3, v39
	s_waitcnt lgkmcnt(0)
	v_add_f32_dpp v40, v40, v40 row_ror:8 row_mask:0xf bank_mask:0xf
	v_add_f32_dpp v41, v41, v41 row_ror:8 row_mask:0xf bank_mask:0xf
	s_nop 1
	s_nop 1
	v_mul_f32_e32 v70, v4, v70
	v_mul_f32_e32 v71, v5, v71
	v_mul_f32_e32 v44, v44, v76
	v_mul_f32_e32 v45, v45, v77
	s_waitcnt lgkmcnt(0)
	v_add_f32_dpp v40, v40, v40 row_ror:4 row_mask:0xf bank_mask:0xf
	v_add_f32_dpp v41, v41, v41 row_ror:4 row_mask:0xf bank_mask:0xf
	s_nop 1
	s_nop 1
	v_mul_f32_e32 v46, v46, v78
	v_mul_f32_e32 v47, v47, v79
	v_mul_f32_e32 v48, v48, v80
	v_mul_f32_e32 v49, v49, v81
	s_waitcnt lgkmcnt(0)
	v_add_f32_dpp v40, v40, v40 row_ror:2 row_mask:0xf bank_mask:0xf
	v_add_f32_dpp v41, v41, v41 row_ror:2 row_mask:0xf bank_mask:0xf
	s_nop 1
	s_nop 1
	v_mul_f32_e32 v50, v50, v82
	v_mul_f32_e32 v51, v51, v83
	s_waitcnt lgkmcnt(0)
	v_add_f32_dpp v40, v40, v40 row_ror:1 row_mask:0xf bank_mask:0xf
	v_add_f32_dpp v41, v41, v41 row_ror:1 row_mask:0xf bank_mask:0xf
	s_nop 1
	s_nop 0
	v_pk_fma_f32 v[40:41], v[40:41], s[18:19], v[20:21] op_sel_hi:[1,0,0]
	s_nop 0
	v_mul_f32_e32 v42, 0x4b800000, v41
	v_cmp_gt_f32_e64 s[4:5], s3, v41
	v_mul_f32_e32 v43, 0x4b800000, v40
	v_cmp_gt_f32_e32 vcc, s3, v40
	v_cndmask_b32_e64 v41, v41, v42, s[4:5]
	v_rsq_f32_e32 v41, v41
	v_cndmask_b32_e32 v40, v40, v43, vcc
	v_rsq_f32_e32 v40, v40
	v_mul_f32_e32 v42, 0x45800000, v41
	v_cndmask_b32_e64 v41, v41, v42, s[4:5]
	v_mul_f32_e32 v43, 0x45800000, v40
	v_cndmask_b32_e32 v40, v40, v43, vcc
	v_mul_f32_e32 v32, v41, v32
	v_mul_f32_e32 v42, v40, v86
	v_mul_f32_e32 v43, v41, v100
	v_mul_f32_e32 v68, v40, v104
	v_mul_f32_e32 v69, v41, v102
	v_mul_f32_e32 v76, v40, v106
	v_mul_f32_e32 v77, v41, v84
	v_mul_f32_e32 v33, v41, v33
	v_fma_f32 v32, v7, v32, v52
	v_mul_f32_e32 v78, v40, v88
	v_mul_f32_e32 v79, v40, v87
	v_mul_f32_e32 v80, v41, v101
	v_mul_f32_e32 v81, v40, v105
	v_mul_f32_e32 v82, v41, v103
	v_mul_f32_e32 v83, v40, v107
	v_mul_f32_e32 v84, v41, v85
	v_mul_f32_e32 v85, v40, v89
	v_mul_f32_e32 v86, v41, v90
	v_mul_f32_e32 v87, v40, v94
	v_mul_f32_e32 v88, v41, v108
	v_mul_f32_e32 v89, v40, v112
	v_mul_f32_e32 v90, v41, v110
	v_mul_f32_e32 v94, v40, v114
	v_mul_f32_e32 v92, v41, v92
	v_mul_f32_e32 v96, v40, v96
	v_mul_f32_e32 v91, v41, v91
	v_mul_f32_e32 v95, v40, v95
	v_mul_f32_e32 v98, v41, v109
	v_mul_f32_e32 v99, v40, v113
	v_mul_f32_e32 v100, v41, v111
	v_mul_f32_e32 v101, v40, v115
	v_mul_f32_e32 v41, v41, v93
	v_mul_f32_e32 v40, v40, v97
	v_fma_f32 v7, v7, v42, v52
	v_fma_f32 v42, v39, v43, v53
	v_fma_f32 v39, v39, v68, v53
	v_fma_f32 v43, v70, v69, v54
	v_fma_f32 v52, v70, v76, v54
	v_fma_f32 v53, v71, v77, v55
	v_fma_f32 v54, v33, v72, v56
	v_cvt_pk_bf16_f32 v32, v32, v42
	v_cvt_pk_bf16_f32 v33, v43, v53
	v_fmac_f32_e32 v55, v71, v78
	v_fma_f32 v56, v79, v72, v56
	v_fma_f32 v68, v80, v73, v57
	v_fma_f32 v57, v81, v73, v57
	v_fma_f32 v69, v82, v74, v58
	v_fma_f32 v58, v83, v74, v58
	v_fma_f32 v70, v84, v75, v59
	v_fmac_f32_e32 v59, v85, v75
	v_fma_f32 v71, v86, v44, v60
	v_fma_f32 v60, v87, v44, v60
	v_fma_f32 v72, v88, v45, v61
	v_fma_f32 v61, v89, v45, v61
	v_fma_f32 v73, v90, v46, v62
	v_fma_f32 v62, v94, v46, v62
	v_fma_f32 v74, v92, v47, v63
	v_fmac_f32_e32 v63, v96, v47
	v_fma_f32 v75, v91, v48, v64
	v_fma_f32 v64, v95, v48, v64
	v_fma_f32 v76, v98, v49, v65
	v_fma_f32 v65, v99, v49, v65
	v_fma_f32 v77, v100, v50, v66
	v_fma_f32 v66, v101, v50, v66
	v_fma_f32 v78, v41, v51, v67
	v_fmac_f32_e32 v67, v40, v51
	v_cvt_pk_bf16_f32 v40, v7, v39
	v_cvt_pk_bf16_f32 v41, v52, v55
	v_cvt_pk_bf16_f32 v42, v54, v68
	v_cvt_pk_bf16_f32 v43, v69, v70
	v_cvt_pk_bf16_f32 v44, v56, v57
	v_cvt_pk_bf16_f32 v45, v58, v59
	v_cvt_pk_bf16_f32 v46, v71, v72
	v_cvt_pk_bf16_f32 v47, v73, v74
	v_cvt_pk_bf16_f32 v48, v60, v61
	v_cvt_pk_bf16_f32 v49, v62, v63
	v_cvt_pk_bf16_f32 v50, v75, v76
	v_cvt_pk_bf16_f32 v51, v77, v78
	v_cvt_pk_bf16_f32 v52, v64, v65
	v_cvt_pk_bf16_f32 v53, v66, v67
	global_store_dwordx2 v[30:31], v[32:33], off
	global_store_dwordx2 v[30:31], v[40:41], off offset:2048
	global_store_dwordx2 v[30:31], v[42:43], off offset:512
	global_store_dwordx2 v[30:31], v[44:45], off offset:2560
	global_store_dwordx2 v[30:31], v[46:47], off offset:1024
	global_store_dwordx2 v[30:31], v[48:49], off offset:3072
	global_store_dwordx2 v[30:31], v[50:51], off offset:1536
	global_store_dwordx2 v[30:31], v[52:53], off offset:3584
	s_andn2_b64 exec, exec, s[16:17]
	s_cbranch_execnz .LBB0_2565

; __device__ __forceinline__ int get_tid() { int t = threadIdx.x & 255; asm volatile("" : "+v"(t)); return t; }
; __device__ __forceinline__ int get_bid() { return 2 * get_rbid() + get_hb(); }
; template <bool PART, bool SRC16 = false>
; __device__ __forceinline__ void normmod_row2(const void* __restrict__ srcv, const float* __restrict__ g, const float* __restrict__ sh, const float* __restrict__ sc, bf16_t* __restrict__ dst, int lane, const float* __restrict__ bsh = nullptr) {
;   f32x4 v[2][4]; float ss0 = 0.f, ss1 = 0.f;
; #pragma unroll
;   for (int i = 0; i < 4; ++i) {
;     if (SRC16) { v[0][i] = ld4_bf16((const bf16_t*)srcv + lane * 4 + 256 * i); v[1][i] = ld4_bf16((const bf16_t*)srcv + 1024 + lane * 4 + 256 * i); }
;     else { v[0][i] = __builtin_nontemporal_load((const f32x4*)((const float*)srcv + lane * 4 + 256 * i)); v[1][i] = __builtin_nontemporal_load((const f32x4*)((const float*)srcv + 1024 + lane * 4 + 256 * i)); }
;   }
; #pragma unroll
;   for (int i = 0; i < 4; ++i) {
;     ss0 += v[0][i][0] * v[0][i][0] + v[0][i][1] * v[0][i][1] + v[0][i][2] * v[0][i][2] + v[0][i][3] * v[0][i][3];
;     ss1 += v[1][i][0] * v[1][i][0] + v[1][i][1] * v[1][i][1] + v[1][i][2] * v[1][i][2] + v[1][i][3] * v[1][i][3];
;   }
;   ss0 = wave_sum(ss0); ss1 = wave_sum(ss1);
; __device__ __forceinline__ void phase_normmod_x(CP& p, const float* g, int layer, int chunk) {
;   const int lane = get_tid() & 63, wv = get_tid() >> 6;
;   for (int r = (get_bid() * 4 + wv) * 2; r < 16384; r += VGRID * 8) {
;     const int b = r >> 11;
;     const float* mv = p.modv + (size_t)(layer * 9 + b) * 6144 + chunk * 1024;
;     normmod_row2<false, true>(p.X16 + (size_t)r * 1024, g, mv, mv + 1024, p.hxc + (size_t)r * 1024, lane);
.LBB0_3342:
	v_lshl_add_u64 v[32:33], v[16:17], 0, v[8:9]
	global_load_dwordx4 v[40:43], v[10:11], off
	global_load_dwordx4 v[44:47], v[12:13], off
	global_load_dwordx4 v[48:51], v[14:15], off
	global_load_dwordx2 v[84:85], v[32:33], off offset:512
	global_load_dwordx2 v[86:87], v[32:33], off
	global_load_dwordx2 v[88:89], v[32:33], off offset:2560
	global_load_dwordx2 v[90:91], v[32:33], off offset:2048
	global_load_dwordx2 v[92:93], v[32:33], off offset:1536
	global_load_dwordx2 v[94:95], v[32:33], off offset:1024
	global_load_dwordx2 v[96:97], v[32:33], off offset:3584
	global_load_dwordx2 v[98:99], v[32:33], off offset:3072
	v_ashrrev_i32_e32 v7, 11, v6
	v_add_u32_e32 v7, 9, v7
	v_mul_hi_i32_i24_e32 v33, 0x6000, v7
	v_mul_i32_i24_e32 v32, 0x6000, v7
	v_lshl_add_u64 v[32:33], s[10:11], 0, v[32:33]
	v_lshl_add_u64 v[68:69], v[32:33], 0, s[8:9]
	v_lshl_add_u64 v[32:33], v[32:33], 0, v[22:23]
	v_lshl_add_u64 v[100:101], v[68:69], 0, v[22:23]
	global_load_dwordx4 v[52:55], v[32:33], off
	global_load_dwordx4 v[56:59], v[32:33], off offset:1024
	v_lshl_add_u64 v[102:103], v[68:69], 0, v[24:25]
	v_lshl_add_u64 v[104:105], v[68:69], 0, v[26:27]
	global_load_dwordx4 v[60:63], v[32:33], off offset:2048
	global_load_dwordx4 v[64:67], v[32:33], off offset:3072
	v_lshl_add_u64 v[32:33], v[68:69], 0, v[28:29]
	global_load_dwordx4 v[68:71], v[100:101], off
	global_load_dwordx4 v[72:75], v[102:103], off
	global_load_dwordx4 v[76:79], v[104:105], off
	global_load_dwordx4 v[80:83], v[32:33], off
	v_add_u32_e32 v6, s12, v6
	v_cmp_lt_i32_e32 vcc, s13, v6
	s_or_b64 s[16:17], vcc, s[16:17]
	v_lshl_add_u64 v[30:31], v[18:19], 0, v[8:9]
	v_lshl_add_u64 v[16:17], v[16:17], 0, s[14:15]
	v_lshl_add_u64 v[18:19], v[18:19], 0, s[14:15]
	s_waitcnt vmcnt(15)
	v_and_b32_e32 v101, 0xffff0000, v84
	s_waitcnt vmcnt(14)
	v_and_b32_e32 v100, 0xffff0000, v86
	s_waitcnt vmcnt(13)
	v_and_b32_e32 v105, 0xffff0000, v88
	s_waitcnt vmcnt(12)
	v_and_b32_e32 v104, 0xffff0000, v90
	v_lshlrev_b32_e32 v33, 16, v84
	v_lshlrev_b32_e32 v32, 16, v86
	v_lshlrev_b32_e32 v102, 16, v87
	v_and_b32_e32 v84, 0xffff0000, v87
	v_lshlrev_b32_e32 v87, 16, v88
	v_lshlrev_b32_e32 v86, 16, v90
	v_lshlrev_b32_e32 v106, 16, v91
	v_and_b32_e32 v88, 0xffff0000, v91
	s_waitcnt vmcnt(11)
	v_lshlrev_b32_e32 v91, 16, v92
	s_waitcnt vmcnt(10)
	v_lshlrev_b32_e32 v90, 16, v94
	v_and_b32_e32 v109, 0xffff0000, v92
	v_and_b32_e32 v108, 0xffff0000, v94
	v_lshlrev_b32_e32 v110, 16, v95
	v_and_b32_e32 v92, 0xffff0000, v95
	s_waitcnt vmcnt(9)
	v_lshlrev_b32_e32 v95, 16, v96
	s_waitcnt vmcnt(8)
	v_lshlrev_b32_e32 v94, 16, v98
	v_and_b32_e32 v113, 0xffff0000, v96
	v_and_b32_e32 v112, 0xffff0000, v98
	v_lshlrev_b32_e32 v114, 16, v99
	v_and_b32_e32 v96, 0xffff0000, v99
	v_pk_mul_f32 v[98:99], v[100:101], v[100:101]
	v_pk_mul_f32 v[116:117], v[104:105], v[104:105]
	v_lshlrev_b32_e32 v103, 16, v85
	v_lshlrev_b32_e32 v107, 16, v89
	v_pk_mul_f32 v[118:119], v[108:109], v[108:109]
	v_pk_mul_f32 v[120:121], v[112:113], v[112:113]
	v_pk_fma_f32 v[98:99], v[32:33], v[32:33], v[98:99]
	v_pk_fma_f32 v[116:117], v[86:87], v[86:87], v[116:117]
	v_and_b32_e32 v85, 0xffff0000, v85
	v_and_b32_e32 v89, 0xffff0000, v89
	v_lshlrev_b32_e32 v111, 16, v93
	v_lshlrev_b32_e32 v115, 16, v97
	v_pk_fma_f32 v[118:119], v[90:91], v[90:91], v[118:119]
	v_pk_fma_f32 v[120:121], v[94:95], v[94:95], v[120:121]
	v_pk_fma_f32 v[98:99], v[102:103], v[102:103], v[98:99]
	v_pk_fma_f32 v[116:117], v[106:107], v[106:107], v[116:117]
	v_and_b32_e32 v93, 0xffff0000, v93
	v_and_b32_e32 v97, 0xffff0000, v97
	v_pk_fma_f32 v[118:119], v[110:111], v[110:111], v[118:119]
	v_pk_fma_f32 v[120:121], v[114:115], v[114:115], v[120:121]
	v_pk_fma_f32 v[98:99], v[84:85], v[84:85], v[98:99]
	v_pk_fma_f32 v[116:117], v[88:89], v[88:89], v[116:117]
	v_pk_fma_f32 v[118:119], v[92:93], v[92:93], v[118:119]
	v_pk_fma_f32 v[120:121], v[96:97], v[96:97], v[120:121]
	v_mov_b32_e32 v122, v116
	v_mov_b32_e32 v123, v98
	v_mov_b32_e32 v98, v117
	v_mov_b32_e32 v116, v120
	v_mov_b32_e32 v117, v118
	s_waitcnt vmcnt(3)
	v_add_f32_e32 v7, 1.0, v68
	v_add_f32_e32 v39, 1.0, v69
	s_waitcnt vmcnt(2)
	v_add_f32_e32 v72, 1.0, v72
	v_add_f32_e32 v73, 1.0, v73
	v_pk_add_f32 v[68:69], v[122:123], v[98:99]
	v_mov_b32_e32 v118, v121
	v_mul_f32_e32 v72, v40, v72
	v_mul_f32_e32 v73, v41, v73
	v_pk_add_f32 v[40:41], v[68:69], v[116:117]
	v_add_f32_e32 v74, 1.0, v74
	v_add_f32_e32 v75, 1.0, v75
	v_pk_add_f32 v[40:41], v[40:41], v[118:119]
	v_mul_f32_e32 v74, v42, v74
	v_mul_f32_e32 v75, v43, v75
	v_mov_b32_e32 v42, v40
	v_mov_b32_e32 v43, v41
	s_nop 1
	v_permlane32_swap_b32 v40, v42
	v_permlane32_swap_b32 v41, v43
	s_nop 1
	v_add_f32_e32 v70, 1.0, v70
	v_add_f32_e32 v71, 1.0, v71
	s_waitcnt vmcnt(1)
	v_add_f32_e32 v76, 1.0, v76
	v_add_f32_e32 v77, 1.0, v77
	s_waitcnt lgkmcnt(0)
; __device__ __forceinline__ unsigned pack2(float a, float b) { unsigned r; asm("v_cvt_pk_bf16_f32 %0, %1, %2" : "=v"(r) : "v"(a), "v"(b)); return r; }
; template <bool PART, bool SRC16 = false>
; __device__ __forceinline__ void normmod_row2(const void* __restrict__ srcv, const float* __restrict__ g, const float* __restrict__ sh, const float* __restrict__ sc, bf16_t* __restrict__ dst, int lane, const float* __restrict__ bsh = nullptr) {
;     ...
;   ss0 = wave_sum(ss0); ss1 = wave_sum(ss1);
;   const float r0 = rsqrtf(ss0 * (1.0f / 1024.0f) + 1e-6f), r1 = rsqrtf(ss1 * (1.0f / 1024.0f) + 1e-6f);
; #pragma unroll
;   for (int i = 0; i < 4; ++i) {
;     const int k = lane * 4 + 256 * i;
;     const f32x4 g4 = *(const f32x4*)(g + k);
;     f32x4 s4 = *(const f32x4*)(sh + k), c4 = *(const f32x4*)(sc + k);
;     if (PART) {
; #pragma unroll
;       for (int q = 1; q < 4; ++q) { s4 += *(const f32x4*)(sh + (size_t)q * 110592 + k); c4 += *(const f32x4*)(sc + (size_t)q * 110592 + k); }
;       s4 += *(const f32x4*)(bsh + k); c4 += *(const f32x4*)(bsh + 1024 + k);
;     }
;     float y[4], z[4];
; #pragma unroll
;     for (int j = 0; j < 4; ++j) { const float gm = g4[j] * (1.f + c4[j]); y[j] = (v[0][i][j] * r0) * gm + s4[j]; z[j] = (v[1][i][j] * r1) * gm + s4[j]; }
;     uint2 u; u.x = pack2(y[0], y[1]); u.y = pack2(y[2], y[3]);
;     *(uint2*)(dst + k) = u;
;     u.x = pack2(z[0], z[1]); u.y = pack2(z[2], z[3]);
;     *(uint2*)(dst + 1024 + k) = u;
	v_pk_add_f32 v[40:41], v[40:41], v[42:43]
	v_mov_b32_e32 v42, v40
	v_mov_b32_e32 v43, v41
	s_nop 1
	v_permlane16_swap_b32 v40, v42
	v_permlane16_swap_b32 v41, v43
	s_nop 1
	v_mul_f32_e32 v7, v2, v7
	v_add_f32_e32 v78, 1.0, v78
	v_add_f32_e32 v79, 1.0, v79
	s_waitcnt vmcnt(0)
	v_add_f32_e32 v80, 1.0, v80
	s_waitcnt lgkmcnt(0)
	v_pk_add_f32 v[40:41], v[40:41], v[42:43]
	s_nop 1
	v_add_f32_e32 v81, 1.0, v81
	v_add_f32_e32 v82, 1.0, v82
	v_add_f32_e32 v83, 1.0, v83
	v_mul_f32_e32 v39, v3, v39
	s_waitcnt lgkmcnt(0)
	v_add_f32_dpp v40, v40, v40 row_ror:8 row_mask:0xf bank_mask:0xf
	v_add_f32_dpp v41, v41, v41 row_ror:8 row_mask:0xf bank_mask:0xf
	s_nop 1
	s_nop 1
	v_mul_f32_e32 v70, v4, v70
	v_mul_f32_e32 v71, v5, v71
	v_mul_f32_e32 v44, v44, v76
	v_mul_f32_e32 v45, v45, v77
	s_waitcnt lgkmcnt(0)
	v_add_f32_dpp v40, v40, v40 row_ror:4 row_mask:0xf bank_mask:0xf
	v_add_f32_dpp v41, v41, v41 row_ror:4 row_mask:0xf bank_mask:0xf
	s_nop 1
	s_nop 1
	v_mul_f32_e32 v46, v46, v78
	v_mul_f32_e32 v47, v47, v79
	v_mul_f32_e32 v48, v48, v80
	v_mul_f32_e32 v49, v49, v81
	s_waitcnt lgkmcnt(0)
	v_add_f32_dpp v40, v40, v40 row_ror:2 row_mask:0xf bank_mask:0xf
	v_add_f32_dpp v41, v41, v41 row_ror:2 row_mask:0xf bank_mask:0xf
	s_nop 1
	s_nop 1
	v_mul_f32_e32 v50, v50, v82
	v_mul_f32_e32 v51, v51, v83
	s_waitcnt lgkmcnt(0)
	v_add_f32_dpp v40, v40, v40 row_ror:1 row_mask:0xf bank_mask:0xf
	v_add_f32_dpp v41, v41, v41 row_ror:1 row_mask:0xf bank_mask:0xf
	s_nop 1
	s_nop 0
	v_pk_fma_f32 v[40:41], v[40:41], s[18:19], v[20:21] op_sel_hi:[1,0,0]
	s_nop 0
	v_mul_f32_e32 v42, 0x4b800000, v41
	v_cmp_gt_f32_e64 s[4:5], s3, v41
	v_mul_f32_e32 v43, 0x4b800000, v40
	v_cmp_gt_f32_e32 vcc, s3, v40
	v_cndmask_b32_e64 v41, v41, v42, s[4:5]
	v_rsq_f32_e32 v41, v41
	v_cndmask_b32_e32 v40, v40, v43, vcc
	v_rsq_f32_e32 v40, v40
	v_mul_f32_e32 v42, 0x45800000, v41
	v_cndmask_b32_e64 v41, v41, v42, s[4:5]
	v_mul_f32_e32 v43, 0x45800000, v40
	v_cndmask_b32_e32 v40, v40, v43, vcc
	v_mul_f32_e32 v32, v41, v32
	v_mul_f32_e32 v42, v40, v86
	v_mul_f32_e32 v43, v41, v100
	v_mul_f32_e32 v68, v40, v104
	v_mul_f32_e32 v69, v41, v102
	v_mul_f32_e32 v76, v40, v106
	v_mul_f32_e32 v77, v41, v84
	v_mul_f32_e32 v33, v41, v33
	v_fma_f32 v32, v7, v32, v52
	v_mul_f32_e32 v78, v40, v88
	v_mul_f32_e32 v79, v40, v87
	v_mul_f32_e32 v80, v41, v101
	v_mul_f32_e32 v81, v40, v105
	v_mul_f32_e32 v82, v41, v103
	v_mul_f32_e32 v83, v40, v107
	v_mul_f32_e32 v84, v41, v85
	v_mul_f32_e32 v85, v40, v89
	v_mul_f32_e32 v86, v41, v90
	v_mul_f32_e32 v87, v40, v94
	v_mul_f32_e32 v88, v41, v108
	v_mul_f32_e32 v89, v40, v112
	v_mul_f32_e32 v90, v41, v110
	v_mul_f32_e32 v94, v40, v114
	v_mul_f32_e32 v92, v41, v92
	v_mul_f32_e32 v96, v40, v96
	v_mul_f32_e32 v91, v41, v91
	v_mul_f32_e32 v95, v40, v95
	v_mul_f32_e32 v98, v41, v109
	v_mul_f32_e32 v99, v40, v113
	v_mul_f32_e32 v100, v41, v111
	v_mul_f32_e32 v101, v40, v115
	v_mul_f32_e32 v41, v41, v93
	v_mul_f32_e32 v40, v40, v97
	v_fma_f32 v7, v7, v42, v52
	v_fma_f32 v42, v39, v43, v53
	v_fma_f32 v39, v39, v68, v53
	v_fma_f32 v43, v70, v69, v54
	v_fma_f32 v52, v70, v76, v54
	v_fma_f32 v53, v71, v77, v55
	v_fma_f32 v54, v33, v72, v56
	v_cvt_pk_bf16_f32 v32, v32, v42
	v_cvt_pk_bf16_f32 v33, v43, v53
	v_fmac_f32_e32 v55, v71, v78
	v_fma_f32 v56, v79, v72, v56
	v_fma_f32 v68, v80, v73, v57
	v_fma_f32 v57, v81, v73, v57
	v_fma_f32 v69, v82, v74, v58
	v_fma_f32 v58, v83, v74, v58
	v_fma_f32 v70, v84, v75, v59
	v_fmac_f32_e32 v59, v85, v75
	v_fma_f32 v71, v86, v44, v60
	v_fma_f32 v60, v87, v44, v60
	v_fma_f32 v72, v88, v45, v61
	v_fma_f32 v61, v89, v45, v61
	v_fma_f32 v73, v90, v46, v62
	v_fma_f32 v62, v94, v46, v62
	v_fma_f32 v74, v92, v47, v63
	v_fmac_f32_e32 v63, v96, v47
	v_fma_f32 v75, v91, v48, v64
	v_fma_f32 v64, v95, v48, v64
	v_fma_f32 v76, v98, v49, v65
	v_fma_f32 v65, v99, v49, v65
	v_fma_f32 v77, v100, v50, v66
	v_fma_f32 v66, v101, v50, v66
	v_fma_f32 v78, v41, v51, v67
	v_fmac_f32_e32 v67, v40, v51
	v_cvt_pk_bf16_f32 v40, v7, v39
	v_cvt_pk_bf16_f32 v41, v52, v55
	v_cvt_pk_bf16_f32 v42, v54, v68
	v_cvt_pk_bf16_f32 v43, v69, v70
	v_cvt_pk_bf16_f32 v44, v56, v57
	v_cvt_pk_bf16_f32 v45, v58, v59
	v_cvt_pk_bf16_f32 v46, v71, v72
	v_cvt_pk_bf16_f32 v47, v73, v74
	v_cvt_pk_bf16_f32 v48, v60, v61
	v_cvt_pk_bf16_f32 v49, v62, v63
	v_cvt_pk_bf16_f32 v50, v75, v76
	v_cvt_pk_bf16_f32 v51, v77, v78
	v_cvt_pk_bf16_f32 v52, v64, v65
	v_cvt_pk_bf16_f32 v53, v66, v67
	global_store_dwordx2 v[30:31], v[32:33], off
	global_store_dwordx2 v[30:31], v[40:41], off offset:2048
	global_store_dwordx2 v[30:31], v[42:43], off offset:512
	global_store_dwordx2 v[30:31], v[44:45], off offset:2560
	global_store_dwordx2 v[30:31], v[46:47], off offset:1024
	global_store_dwordx2 v[30:31], v[48:49], off offset:3072
	global_store_dwordx2 v[30:31], v[50:51], off offset:1536
	global_store_dwordx2 v[30:31], v[52:53], off offset:3584
	s_andn2_b64 exec, exec, s[16:17]
	s_cbranch_execnz .LBB0_3342

; __device__ __forceinline__ int get_tid() { int t = threadIdx.x & 255; asm volatile("" : "+v"(t)); return t; }
; __device__ __forceinline__ int get_bid() { return 2 * get_rbid() + get_hb(); }
; __device__ __forceinline__ void phase_final_norm(CP& p) {
;   const int lane = get_tid() & 63, wv = get_tid() >> 6;
;   for (int r = get_bid() * 4 + wv; r < 16384; r += VGRID * 4) {
;     const bf16_t* srow = p.X16 + (size_t)r * 1024;
;     float* row = p.X + (size_t)r * 1024;
;     f32x4 v[4]; float ss = 0.f;
; #pragma unroll
;     for (int i = 0; i < 4; ++i) { v[i] = ld4_bf16(srow + lane * 4 + 256 * i); ss += v[i][0] * v[i][0] + v[i][1] * v[i][1] + v[i][2] * v[i][2] + v[i][3] * v[i][3]; }
;     ss = wave_sum(ss);
;     const float rr = rsqrtf(ss * (1.0f / 1024.0f) + 1e-6f);
; #pragma unroll
;     for (int i = 0; i < 4; ++i) {
;       const int k = lane * 4 + 256 * i;
;       const f32x4 g4 = *(const f32x4*)(p.final_g + k);
;       f32x4 o; o[0] = v[i][0] * rr * g4[0]; o[1] = v[i][1] * rr * g4[1]; o[2] = v[i][2] * rr * g4[2]; o[3] = v[i][3] * rr * g4[3];
;       __builtin_nontemporal_store(o, (f32x4*)(row + k));
;     }
;   }
; }
.LBB0_3652:
	global_load_dwordx2 v[20:21], v[6:7], off offset:-1540
	global_load_dwordx2 v[22:23], v[6:7], off offset:-1028
	global_load_dwordx2 v[24:25], v[6:7], off offset:-516
	global_load_dwordx2 v[26:27], v[6:7], off offset:-4
	v_add_u32_e32 v2, s0, v2
	v_lshl_add_u64 v[6:7], v[6:7], 0, s[4:5]
	s_waitcnt vmcnt(3)
	v_and_b32_e32 v29, 0xffff0000, v20
	v_lshlrev_b32_e32 v28, 16, v20
	s_waitcnt vmcnt(2)
	v_and_b32_e32 v33, 0xffff0000, v22
	s_waitcnt vmcnt(1)
	v_and_b32_e32 v37, 0xffff0000, v24
	v_mov_b32_e32 v32, v29
	v_lshlrev_b32_e32 v20, 16, v21
	v_lshlrev_b32_e32 v31, 16, v22
	v_lshlrev_b32_e32 v36, 16, v24
	s_waitcnt vmcnt(0)
	v_and_b32_e32 v41, 0xffff0000, v26
	v_mov_b32_e32 v30, v28
	v_mov_b32_e32 v40, v37
	v_pk_mul_f32 v[44:45], v[32:33], v[32:33]
	v_and_b32_e32 v21, 0xffff0000, v21
	v_lshlrev_b32_e32 v35, 16, v23
	v_lshlrev_b32_e32 v24, 16, v25
	v_lshlrev_b32_e32 v39, 16, v26
	v_mov_b32_e32 v34, v20
	v_mov_b32_e32 v38, v36
	v_pk_mul_f32 v[46:47], v[40:41], v[40:41]
	v_pk_fma_f32 v[44:45], v[30:31], v[30:31], v[44:45]
	v_and_b32_e32 v23, 0xffff0000, v23
	v_and_b32_e32 v25, 0xffff0000, v25
	v_lshlrev_b32_e32 v43, 16, v27
	v_mov_b32_e32 v22, v21
	v_mov_b32_e32 v42, v24
	v_pk_fma_f32 v[46:47], v[38:39], v[38:39], v[46:47]
	v_pk_fma_f32 v[44:45], v[34:35], v[34:35], v[44:45]
	v_and_b32_e32 v27, 0xffff0000, v27
	v_mov_b32_e32 v26, v25
	v_pk_fma_f32 v[46:47], v[42:43], v[42:43], v[46:47]
	v_pk_fma_f32 v[44:45], v[22:23], v[22:23], v[44:45]
	v_pk_fma_f32 v[46:47], v[26:27], v[26:27], v[46:47]
	v_add_f32_e32 v22, v44, v45
	v_add_f32_e32 v22, v22, v46
	v_add_f32_e32 v22, v22, v47
	v_mov_b32_e32 v26, v22
	s_nop 1
	v_permlane32_swap_b32 v22, v26
	s_nop 1
	v_mov_b32_e32 v32, v31
	v_mov_b32_e32 v40, v39
	s_waitcnt lgkmcnt(0)
	v_add_f32_e32 v22, v22, v26
	v_mov_b32_e32 v26, v22
	s_nop 1
	v_permlane16_swap_b32 v22, v26
	s_nop 1
	s_waitcnt lgkmcnt(0)
	v_add_f32_e32 v22, v22, v26
	s_nop 1
	s_waitcnt lgkmcnt(0)
	v_add_f32_dpp v22, v22, v22 row_ror:8 row_mask:0xf bank_mask:0xf
	s_nop 1
	s_nop 1
	s_waitcnt lgkmcnt(0)
	v_add_f32_dpp v22, v22, v22 row_ror:4 row_mask:0xf bank_mask:0xf
	s_nop 1
	s_nop 1
	s_waitcnt lgkmcnt(0)
	v_add_f32_dpp v22, v22, v22 row_ror:2 row_mask:0xf bank_mask:0xf
	s_nop 1
	s_nop 1
	s_waitcnt lgkmcnt(0)
	v_add_f32_dpp v22, v22, v22 row_ror:1 row_mask:0xf bank_mask:0xf
	s_nop 1
	v_fmamk_f32 v22, v22, 0x3a800000, v3
	v_mul_f32_e32 v26, 0x4b800000, v22
	v_cmp_gt_f32_e32 vcc, s1, v22
	s_nop 1
	v_cndmask_b32_e32 v22, v22, v26, vcc
	v_rsq_f32_e32 v22, v22
	s_nop 0
	v_mul_f32_e32 v26, 0x45800000, v22
	v_cndmask_b32_e32 v30, v22, v26, vcc
	v_pk_mul_f32 v[28:29], v[30:31], v[28:29] op_sel_hi:[0,1]
	v_pk_mul_f32 v[20:21], v[30:31], v[20:21] op_sel_hi:[0,1]
	v_pk_mul_f32 v[18:19], v[50:51], v[20:21]
	v_pk_mul_f32 v[16:17], v[48:49], v[28:29]
	global_store_dwordx4 v[8:9], v[16:19], off offset:-3072 nt
	v_mov_b32_e32 v22, v35
	v_pk_mul_f32 v[20:21], v[30:31], v[22:23] op_sel_hi:[0,1]
	v_pk_mul_f32 v[22:23], v[30:31], v[32:33] op_sel_hi:[0,1]
	v_mov_b32_e32 v26, v43
	v_cmp_lt_i32_e32 vcc, s10, v2
	s_or_b64 s[8:9], vcc, s[8:9]
	v_pk_mul_f32 v[16:17], v[52:53], v[22:23]
	v_pk_mul_f32 v[18:19], v[54:55], v[20:21]
	global_store_dwordx4 v[8:9], v[16:19], off offset:-2048 nt
	v_pk_mul_f32 v[20:21], v[30:31], v[24:25] op_sel_hi:[0,1]
	v_pk_mul_f32 v[22:23], v[30:31], v[36:37] op_sel_hi:[0,1]
	v_pk_mul_f32 v[16:17], v[56:57], v[22:23]
	v_pk_mul_f32 v[18:19], v[58:59], v[20:21]
	global_store_dwordx4 v[8:9], v[16:19], off offset:-1024 nt
	v_pk_mul_f32 v[20:21], v[30:31], v[26:27] op_sel_hi:[0,1]
	v_pk_mul_f32 v[22:23], v[30:31], v[40:41] op_sel_hi:[0,1]
	v_pk_mul_f32 v[16:17], v[60:61], v[22:23]
	v_pk_mul_f32 v[18:19], v[62:63], v[20:21]
	global_store_dwordx4 v[8:9], v[16:19], off nt
	v_lshl_add_u64 v[8:9], v[8:9], 0, s[6:7]
	s_andn2_b64 exec, exec, s[8:9]
	s_cbranch_execnz .LBB0_3652
